# attn fast path: per-tile row-max chain dropped, guarded by per-lane partial-sum check that falls back to the original tile body; plus down gemm saddr loads and GU LDS base precompute
# speedup vs baseline: 1.0190x; 1.0142x over previous
; __device__ __forceinline__ void phase_attn(const Params& p, int S, int lgS, int B, int* counter, LAS unsigned char* lds) {
;     ...
;         for (int t = 0; t < NT; ++t) {
;             const LAS unsigned char* kb = lds + (t & 1) * BUFB; const LAS unsigned char* vb = kb + KB;
;             if (t + 1 < NT) { const bf16_t* kn = ksrc + (size_t)(t + 1) * 128 * 2048; const bf16_t* vn_ = vsrc + (t + 1) * 128;
;                 kreg0 = *(const u32x4*)kn; kreg1 = *(const u32x4*)(kn + (size_t)64 * 2048); vreg0 = *(const u32x4*)vn_; vreg1 = *(const u32x4*)(vn_ + 64); }
;             f32x16 pp[4] = {negm, negm, negm, negm};
;             const LAS unsigned char* kl = kb + klane; const LAS unsigned char* vl = vb + vlane;
; #pragma unroll
;             for (int d0 = 0; d0 < 4; ++d0)
; #pragma unroll
;                 for (int j = 0; j < 4; ++j) { const bf16x8 a = *(const LAS bf16x8*)(kl + (32 * j * 72 + 16 * d0) * 2); pp[j] = __builtin_amdgcn_mfma_f32_32x32x16_bf16(a, qr[d0], pp[j], 0, 0, 0); }
;             float mxa = fmaxf(pp[0][0], pp[1][0]), mxb = fmaxf(pp[2][0], pp[3][0]);
; #pragma unroll
;             for (int r = 1; r < 16; ++r) { mxa = fmaxf(fmaxf(mxa, pp[0][r]), pp[1][r]); mxb = fmaxf(fmaxf(mxb, pp[2][r]), pp[3][r]); }
;             float mx = fmaxf(mxa, mxb);
;             mx = fmaxf(mx, shx(mx, 32, lane));
;             const bool first = (t == 0);
;             if (first || __any(mx > 8.f)) {
;                 const float d = first ? mx : fmaxf(mx, 0.f);
;                 m_run += d;
; #pragma unroll
;                 for (int j = 0; j < 4; ++j)
; #pragma unroll
;                     for (int r = 0; r < 16; ++r) pp[j][r] -= d;
; #pragma unroll
;                 for (int r = 0; r < 16; ++r) negm[r] = -m_run;
;                 if (!first) {
;                     const float alpha = __builtin_amdgcn_exp2f(-d); l_run *= alpha;
;                     if (hi == 0) wsf[r32] = alpha;
;                     LDS_WAIT();
; #pragma unroll
;                     for (int r = 0; r < 16; ++r) { const float f = wsf[crow(r, hi)]; o0[r] *= f; o1[r] *= f; }
;                     LDS_WAIT();
;                 }
;             }
;             float ls = 0.f;
; #pragma unroll
;             for (int j = 0; j < 4; ++j)
; #pragma unroll
;                 for (int r = 0; r < 16; ++r) { pp[j][r] = __builtin_amdgcn_exp2f(pp[j][r]); ls += pp[j][r]; }
;             l_run += ls;
.LBB0_731:
	s_bitcmp1_b32 s18, 0
	s_cselect_b32 s18, 0x8c00, 0
	s_add_i32 s18, s18, 0
	v_add_u32_e32 v155, s18, v198
	ds_read_b128 v[224:227], v155
	ds_read_b128 v[228:231], v155 offset:4608
	ds_read_b128 v[232:235], v155 offset:9216
	ds_read_b128 v[242:245], v155 offset:13824
	s_mov_b32 s19, 0x43800000
	s_waitcnt lgkmcnt(3)
	v_mfma_f32_32x32x16_bf16 v[96:111], v[224:227], v[112:115], v[32:47]
	ds_read_b128 v[224:227], v155 offset:32
	s_waitcnt lgkmcnt(3)
	v_mfma_f32_32x32x16_bf16 v[80:95], v[228:231], v[112:115], v[32:47]
	ds_read_b128 v[228:231], v155 offset:4640
	s_waitcnt lgkmcnt(3)
	v_mfma_f32_32x32x16_bf16 v[64:79], v[232:235], v[112:115], v[32:47]
	ds_read_b128 v[232:235], v155 offset:9248
	s_waitcnt lgkmcnt(3)
	v_mfma_f32_32x32x16_bf16 v[48:63], v[242:245], v[112:115], v[32:47]
	ds_read_b128 v[242:245], v155 offset:13856
	s_waitcnt lgkmcnt(3)
	v_mfma_f32_32x32x16_bf16 v[96:111], v[224:227], v[116:119], v[96:111]
	ds_read_b128 v[224:227], v155 offset:64
	s_waitcnt lgkmcnt(3)
	v_mfma_f32_32x32x16_bf16 v[80:95], v[228:231], v[116:119], v[80:95]
	ds_read_b128 v[228:231], v155 offset:4672
	s_waitcnt lgkmcnt(3)
	v_mfma_f32_32x32x16_bf16 v[64:79], v[232:235], v[116:119], v[64:79]
	ds_read_b128 v[232:235], v155 offset:9280
	s_waitcnt lgkmcnt(3)
	v_mfma_f32_32x32x16_bf16 v[48:63], v[242:245], v[116:119], v[48:63]
	ds_read_b128 v[242:245], v155 offset:13888
	s_waitcnt lgkmcnt(3)
	v_mfma_f32_32x32x16_bf16 v[96:111], v[224:227], v[120:123], v[96:111]
	ds_read_b128 v[224:227], v155 offset:96
	s_waitcnt lgkmcnt(3)
	v_mfma_f32_32x32x16_bf16 v[80:95], v[228:231], v[120:123], v[80:95]
	ds_read_b128 v[228:231], v155 offset:4704
	s_waitcnt lgkmcnt(3)
	v_mfma_f32_32x32x16_bf16 v[64:79], v[232:235], v[120:123], v[64:79]
	ds_read_b128 v[232:235], v155 offset:9312
	s_waitcnt lgkmcnt(3)
	v_mfma_f32_32x32x16_bf16 v[48:63], v[242:245], v[120:123], v[48:63]
	ds_read_b128 v[242:245], v155 offset:13920
	s_waitcnt lgkmcnt(3)
	v_mfma_f32_32x32x16_bf16 v[96:111], v[224:227], v[124:127], v[96:111]
	s_waitcnt lgkmcnt(2)
	v_mfma_f32_32x32x16_bf16 v[80:95], v[228:231], v[124:127], v[80:95]
	s_waitcnt lgkmcnt(1)
	v_mfma_f32_32x32x16_bf16 v[64:79], v[232:235], v[124:127], v[64:79]
	s_waitcnt lgkmcnt(0)
	v_mfma_f32_32x32x16_bf16 v[48:63], v[242:245], v[124:127], v[48:63]
	v_add3_u32 v155, s18, v186, v199
	v_add_u32_e32 v157, 0x4800, v155
	v_add_u32_e32 v155, 0x6800, v155
	ds_read_b128 v[228:231], v157
	ds_read_b128 v[232:235], v155 offset:512
	ds_read_b128 v[242:245], v157 offset:32
	s_nop 0
	v_exp_f32_e32 v96, v96
	v_exp_f32_e32 v97, v97
	v_exp_f32_e32 v98, v98
	v_exp_f32_e32 v99, v99
	v_exp_f32_e32 v100, v100
	v_exp_f32_e32 v101, v101
	v_exp_f32_e32 v102, v102
	v_exp_f32_e32 v103, v103
	v_exp_f32_e32 v104, v104
	v_exp_f32_e32 v105, v105
	v_exp_f32_e32 v106, v106
	v_exp_f32_e32 v107, v107
	v_exp_f32_e32 v108, v108
	v_exp_f32_e32 v109, v109
	v_exp_f32_e32 v110, v110
	v_exp_f32_e32 v111, v111
	v_exp_f32_e32 v80, v80
	v_exp_f32_e32 v81, v81
	v_exp_f32_e32 v82, v82
	v_exp_f32_e32 v83, v83
	v_exp_f32_e32 v84, v84
	v_exp_f32_e32 v85, v85
	v_exp_f32_e32 v86, v86
	v_exp_f32_e32 v87, v87
	v_exp_f32_e32 v88, v88
	v_exp_f32_e32 v89, v89
	v_exp_f32_e32 v90, v90
	v_exp_f32_e32 v91, v91
	v_exp_f32_e32 v92, v92
	v_exp_f32_e32 v93, v93
	v_exp_f32_e32 v94, v94
	v_exp_f32_e32 v95, v95
	v_exp_f32_e32 v64, v64
	v_exp_f32_e32 v65, v65
	v_exp_f32_e32 v66, v66
	v_exp_f32_e32 v67, v67
	v_exp_f32_e32 v68, v68
	v_exp_f32_e32 v69, v69
	v_exp_f32_e32 v70, v70
	v_exp_f32_e32 v71, v71
	v_exp_f32_e32 v72, v72
	v_exp_f32_e32 v73, v73
	v_exp_f32_e32 v74, v74
	v_exp_f32_e32 v75, v75
	v_exp_f32_e32 v76, v76
	v_exp_f32_e32 v77, v77
	v_exp_f32_e32 v78, v78
	v_exp_f32_e32 v79, v79
	v_exp_f32_e32 v48, v48
	v_exp_f32_e32 v49, v49
	v_exp_f32_e32 v50, v50
	v_exp_f32_e32 v51, v51
	v_exp_f32_e32 v52, v52
	v_exp_f32_e32 v53, v53
	v_exp_f32_e32 v54, v54
	v_exp_f32_e32 v55, v55
	v_exp_f32_e32 v56, v56
	v_exp_f32_e32 v57, v57
	v_exp_f32_e32 v58, v58
	v_exp_f32_e32 v59, v59
	v_exp_f32_e32 v60, v60
	v_exp_f32_e32 v61, v61
	v_exp_f32_e32 v62, v62
	v_exp_f32_e32 v63, v63
	v_add_f32_e32 v236, v97, v96
	v_add_f32_e32 v236, v98, v236
	v_add_f32_e32 v236, v99, v236
	v_add_f32_e32 v236, v100, v236
	v_add_f32_e32 v236, v101, v236
	v_add_f32_e32 v236, v102, v236
	v_add_f32_e32 v236, v103, v236
	v_add_f32_e32 v236, v104, v236
	v_add_f32_e32 v236, v105, v236
	v_add_f32_e32 v236, v106, v236
	v_add_f32_e32 v236, v107, v236
	v_add_f32_e32 v236, v108, v236
	v_add_f32_e32 v236, v109, v236
	v_add_f32_e32 v236, v110, v236
	v_add_f32_e32 v236, v111, v236
	v_add_f32_e32 v236, v80, v236
	v_add_f32_e32 v236, v81, v236
	v_add_f32_e32 v236, v82, v236
	v_add_f32_e32 v236, v83, v236
	v_add_f32_e32 v236, v84, v236
	v_add_f32_e32 v236, v85, v236
	v_add_f32_e32 v236, v86, v236
	v_add_f32_e32 v236, v87, v236
	v_add_f32_e32 v236, v88, v236
	v_add_f32_e32 v236, v89, v236
	v_add_f32_e32 v236, v90, v236
	v_add_f32_e32 v236, v91, v236
	v_add_f32_e32 v236, v92, v236
	v_add_f32_e32 v236, v93, v236
	v_add_f32_e32 v236, v94, v236
	v_add_f32_e32 v236, v95, v236
	v_add_f32_e32 v236, v64, v236
	v_add_f32_e32 v236, v65, v236
	v_add_f32_e32 v236, v66, v236
	v_add_f32_e32 v236, v67, v236
	v_add_f32_e32 v236, v68, v236
	v_add_f32_e32 v236, v69, v236
	v_add_f32_e32 v236, v70, v236
	v_add_f32_e32 v236, v71, v236
	v_add_f32_e32 v236, v72, v236
	v_add_f32_e32 v236, v73, v236
	v_add_f32_e32 v236, v74, v236
	v_add_f32_e32 v236, v75, v236
	v_add_f32_e32 v236, v76, v236
	v_add_f32_e32 v236, v77, v236
	v_add_f32_e32 v236, v78, v236
	v_add_f32_e32 v236, v79, v236
	v_add_f32_e32 v236, v48, v236
	v_add_f32_e32 v236, v49, v236
	v_add_f32_e32 v236, v50, v236
	v_add_f32_e32 v236, v51, v236
	v_add_f32_e32 v236, v52, v236
	v_add_f32_e32 v236, v53, v236
	v_add_f32_e32 v236, v54, v236
	v_add_f32_e32 v236, v55, v236
	v_add_f32_e32 v236, v56, v236
	v_add_f32_e32 v236, v57, v236
	v_add_f32_e32 v236, v58, v236
	v_add_f32_e32 v236, v59, v236
	v_add_f32_e32 v236, v60, v236
	v_add_f32_e32 v236, v61, v236
	v_add_f32_e32 v236, v62, v236
	v_add_f32_e32 v236, v63, v236
	v_cmp_lt_f32_e32 vcc, s19, v236
	s_cbranch_vccnz .Latt_slow
; #define LAS __attribute__((address_space(3)))
; __device__ __forceinline__ void phase_attn(const Params& p, int S, int lgS, int B, int* counter, LAS unsigned char* lds) {
;     ...
;         for (int t = 0; t < NT; ++t) {
;             const LAS unsigned char* kb = lds + (t & 1) * BUFB; const LAS unsigned char* vb = kb + KB;
;             if (t + 1 < NT) { const bf16_t* kn = ksrc + (size_t)(t + 1) * 128 * 2048; const bf16_t* vn_ = vsrc + (t + 1) * 128;
;                 kreg0 = *(const u32x4*)kn; kreg1 = *(const u32x4*)(kn + (size_t)64 * 2048); vreg0 = *(const u32x4*)vn_; vreg1 = *(const u32x4*)(vn_ + 64); }
;             f32x16 pp[4] = {negm, negm, negm, negm};
;             const LAS unsigned char* kl = kb + klane; const LAS unsigned char* vl = vb + vlane;
; #pragma unroll
;             for (int d0 = 0; d0 < 4; ++d0)
; #pragma unroll
;                 for (int j = 0; j < 4; ++j) { const bf16x8 a = *(const LAS bf16x8*)(kl + (32 * j * 72 + 16 * d0) * 2); pp[j] = __builtin_amdgcn_mfma_f32_32x32x16_bf16(a, qr[d0], pp[j], 0, 0, 0); }
;     ...
; #pragma unroll
;             for (int j = 0; j < 4; ++j)
; #pragma unroll
;                 for (int kk = 0; kk < 2; ++kk) {
;                     const int ks = 2 * j + kk;
;                     const bf16x8 pa = pack8(pp[j][8 * kk], pp[j][8 * kk + 1], pp[j][8 * kk + 2], pp[j][8 * kk + 3], pp[j][8 * kk + 4], pp[j][8 * kk + 5], pp[j][8 * kk + 6], pp[j][8 * kk + 7]);
;                     const u32x2 v0a = *(const LAS u32x2*)(vl + (16 * ks) * 2), v0b = *(const LAS u32x2*)(vl + (16 * ks + 8) * 2);
;                     const u32x2 v1a = *(const LAS u32x2*)(vl + (32 * 136 + 16 * ks) * 2), v1b = *(const LAS u32x2*)(vl + (32 * 136 + 16 * ks + 8) * 2);
;                     const u32x4 f0 = {v0a.x, v0a.y, v0b.x, v0b.y}, f1 = {v1a.x, v1a.y, v1b.x, v1b.y};
;                     o0 = __builtin_amdgcn_mfma_f32_32x32x16_bf16(pa, __builtin_bit_cast(bf16x8, f0), o0, 0, 0, 0);
;                     o1 = __builtin_amdgcn_mfma_f32_32x32x16_bf16(pa, __builtin_bit_cast(bf16x8, f1), o1, 0, 0, 0);
;                 }
;             if (t + 1 < NT) { LAS unsigned char* nb = lds + ((t + 1) & 1) * BUFB;
;                 *(LAS u32x4*)(nb + kdst) = kreg0; *(LAS u32x4*)(nb + kdst + 64 * 144) = kreg1; *(LAS u32x4*)(nb + vdst) = vreg0; *(LAS u32x4*)(nb + vdst + 128) = vreg1; }
;             __syncthreads();
	v_cvt_pk_bf16_f32 v224, v96, v97
	v_cvt_pk_bf16_f32 v225, v98, v99
	v_cvt_pk_bf16_f32 v226, v100, v101
	v_cvt_pk_bf16_f32 v227, v102, v103
	v_add_f32_e32 v195, v195, v236
	s_waitcnt lgkmcnt(1)
	v_mfma_f32_32x32x16_bf16 v[0:15], v[224:227], v[228:231], v[0:15]
	ds_read_b128 v[228:231], v155 offset:544
	v_mfma_f32_32x32x16_bf16 v[16:31], v[224:227], v[232:235], v[16:31]
	v_cvt_pk_bf16_f32 v224, v104, v105
	v_cvt_pk_bf16_f32 v225, v106, v107
	v_cvt_pk_bf16_f32 v226, v108, v109
	v_cvt_pk_bf16_f32 v227, v110, v111
	ds_read_b128 v[232:235], v157 offset:64
	s_waitcnt lgkmcnt(1)
	v_mfma_f32_32x32x16_bf16 v[0:15], v[224:227], v[242:245], v[0:15]
	ds_read_b128 v[242:245], v155 offset:576
	v_mfma_f32_32x32x16_bf16 v[16:31], v[224:227], v[228:231], v[16:31]
	v_cvt_pk_bf16_f32 v224, v80, v81
	v_cvt_pk_bf16_f32 v225, v82, v83
	v_cvt_pk_bf16_f32 v226, v84, v85
	v_cvt_pk_bf16_f32 v227, v86, v87
	ds_read_b128 v[228:231], v157 offset:96
	s_waitcnt lgkmcnt(1)
	v_mfma_f32_32x32x16_bf16 v[0:15], v[224:227], v[232:235], v[0:15]
	ds_read_b128 v[232:235], v155 offset:608
	v_mfma_f32_32x32x16_bf16 v[16:31], v[224:227], v[242:245], v[16:31]
	v_cvt_pk_bf16_f32 v224, v88, v89
	v_cvt_pk_bf16_f32 v225, v90, v91
	v_cvt_pk_bf16_f32 v226, v92, v93
	v_cvt_pk_bf16_f32 v227, v94, v95
	ds_read_b128 v[242:245], v157 offset:128
	s_waitcnt lgkmcnt(1)
	v_mfma_f32_32x32x16_bf16 v[0:15], v[224:227], v[228:231], v[0:15]
	ds_read_b128 v[228:231], v155 offset:640
	v_mfma_f32_32x32x16_bf16 v[16:31], v[224:227], v[232:235], v[16:31]
	v_cvt_pk_bf16_f32 v224, v64, v65
	v_cvt_pk_bf16_f32 v225, v66, v67
	v_cvt_pk_bf16_f32 v226, v68, v69
	v_cvt_pk_bf16_f32 v227, v70, v71
	ds_read_b128 v[232:235], v157 offset:160
	s_waitcnt lgkmcnt(1)
	v_mfma_f32_32x32x16_bf16 v[0:15], v[224:227], v[242:245], v[0:15]
	ds_read_b128 v[242:245], v155 offset:672
	v_mfma_f32_32x32x16_bf16 v[16:31], v[224:227], v[228:231], v[16:31]
	v_cvt_pk_bf16_f32 v224, v72, v73
	v_cvt_pk_bf16_f32 v225, v74, v75
	v_cvt_pk_bf16_f32 v226, v76, v77
	v_cvt_pk_bf16_f32 v227, v78, v79
	ds_read_b128 v[228:231], v157 offset:192
	s_waitcnt lgkmcnt(1)
	v_mfma_f32_32x32x16_bf16 v[0:15], v[224:227], v[232:235], v[0:15]
	ds_read_b128 v[232:235], v155 offset:704
	v_mfma_f32_32x32x16_bf16 v[16:31], v[224:227], v[242:245], v[16:31]
	v_cvt_pk_bf16_f32 v224, v48, v49
	v_cvt_pk_bf16_f32 v225, v50, v51
	v_cvt_pk_bf16_f32 v226, v52, v53
	v_cvt_pk_bf16_f32 v227, v54, v55
	ds_read_b128 v[242:245], v157 offset:224
	s_waitcnt lgkmcnt(1)
	v_mfma_f32_32x32x16_bf16 v[0:15], v[224:227], v[228:231], v[0:15]
	ds_read_b128 v[228:231], v155 offset:736
	v_mfma_f32_32x32x16_bf16 v[16:31], v[224:227], v[232:235], v[16:31]
	v_cvt_pk_bf16_f32 v224, v56, v57
	v_cvt_pk_bf16_f32 v225, v58, v59
	v_cvt_pk_bf16_f32 v226, v60, v61
	v_cvt_pk_bf16_f32 v227, v62, v63
	s_andn2_b64 vcc, exec, s[26:27]
	s_waitcnt lgkmcnt(0)
	v_mfma_f32_32x32x16_bf16 v[0:15], v[224:227], v[242:245], v[0:15]
	v_mfma_f32_32x32x16_bf16 v[16:31], v[224:227], v[228:231], v[16:31]
	s_cbranch_vccnz .Latt_fast_nowr
	s_bitcmp1_b32 s17, 0
	s_cselect_b32 s18, 0x8c00, 0
	v_add_u32_e32 v155, s18, v145
	v_add_u32_e32 v157, s18, v149
	s_waitcnt vmcnt(3)
	ds_write_b128 v155, v[128:131]
	s_waitcnt vmcnt(2)
	ds_write_b128 v155, v[132:135] offset:9216
	s_waitcnt vmcnt(1)
	ds_write2_b64 v157, v[136:137], v[138:139] offset1:2
	s_waitcnt vmcnt(0)
	ds_write2_b64 v157, v[140:141], v[142:143] offset0:16 offset1:18
.Latt_fast_nowr:
	s_addk_i32 s96, 0x80
	s_mov_b64 s[18:19], 0x80000
	s_cmp_eq_u32 s93, s17
	v_lshl_add_u64 v[192:193], v[192:193], 0, s[18:19]
	s_waitcnt lgkmcnt(0)
	s_barrier
	s_cbranch_scc1 .LBB0_739
	s_mov_b32 s18, s17
	s_branch .LBB0_729
.Latt_slow:
	v_add_u32_e32 v155, s18, v198
	ds_read_b128 v[224:227], v155
	ds_read_b128 v[228:231], v155 offset:4608
	ds_read_b128 v[232:235], v155 offset:9216
	ds_read_b128 v[242:245], v155 offset:13824
	s_mov_b32 s19, 0x41000000
	s_waitcnt lgkmcnt(3)
	v_mfma_f32_32x32x16_bf16 v[96:111], v[224:227], v[112:115], v[32:47]
	ds_read_b128 v[224:227], v155 offset:32
	s_waitcnt lgkmcnt(3)
	v_mfma_f32_32x32x16_bf16 v[80:95], v[228:231], v[112:115], v[32:47]
	ds_read_b128 v[228:231], v155 offset:4640
	s_waitcnt lgkmcnt(3)
	v_mfma_f32_32x32x16_bf16 v[64:79], v[232:235], v[112:115], v[32:47]
	ds_read_b128 v[232:235], v155 offset:9248
	s_waitcnt lgkmcnt(3)
	v_mfma_f32_32x32x16_bf16 v[48:63], v[242:245], v[112:115], v[32:47]
	ds_read_b128 v[242:245], v155 offset:13856
	s_waitcnt lgkmcnt(3)
	v_mfma_f32_32x32x16_bf16 v[96:111], v[224:227], v[116:119], v[96:111]
	ds_read_b128 v[224:227], v155 offset:64
	s_waitcnt lgkmcnt(3)
	v_mfma_f32_32x32x16_bf16 v[80:95], v[228:231], v[116:119], v[80:95]
	ds_read_b128 v[228:231], v155 offset:4672
	s_waitcnt lgkmcnt(3)
	v_mfma_f32_32x32x16_bf16 v[64:79], v[232:235], v[116:119], v[64:79]
	ds_read_b128 v[232:235], v155 offset:9280
	s_waitcnt lgkmcnt(3)
	v_mfma_f32_32x32x16_bf16 v[48:63], v[242:245], v[116:119], v[48:63]
	ds_read_b128 v[242:245], v155 offset:13888
	s_waitcnt lgkmcnt(3)
	v_mfma_f32_32x32x16_bf16 v[96:111], v[224:227], v[120:123], v[96:111]
	ds_read_b128 v[224:227], v155 offset:96
	s_waitcnt lgkmcnt(3)
	v_mfma_f32_32x32x16_bf16 v[80:95], v[228:231], v[120:123], v[80:95]
	ds_read_b128 v[228:231], v155 offset:4704
	s_waitcnt lgkmcnt(3)
	v_mfma_f32_32x32x16_bf16 v[64:79], v[232:235], v[120:123], v[64:79]
	ds_read_b128 v[232:235], v155 offset:9312
	s_waitcnt lgkmcnt(3)
	v_mfma_f32_32x32x16_bf16 v[48:63], v[242:245], v[120:123], v[48:63]
	ds_read_b128 v[242:245], v155 offset:13920
	s_waitcnt lgkmcnt(3)
	v_mfma_f32_32x32x16_bf16 v[96:111], v[224:227], v[124:127], v[96:111]
	s_waitcnt lgkmcnt(2)
	v_mfma_f32_32x32x16_bf16 v[80:95], v[228:231], v[124:127], v[80:95]
	s_waitcnt lgkmcnt(1)
; #define LDS_WAIT() asm volatile("s_waitcnt lgkmcnt(0)" ::: "memory")
; __device__ __forceinline__ float shx(float v, int mask, int lane) { return __int_as_float(__builtin_amdgcn_ds_bpermute((lane ^ mask) << 2, __float_as_int(v))); }
; __device__ __forceinline__ int crow(int r, int hi) { return (r & 3) + 8 * (r >> 2) + 4 * hi; }
; __device__ __forceinline__ void phase_attn(const Params& p, int S, int lgS, int B, int* counter, LAS unsigned char* lds) {
;     ...
;             float mxa = fmaxf(pp[0][0], pp[1][0]), mxb = fmaxf(pp[2][0], pp[3][0]);
; #pragma unroll
;             for (int r = 1; r < 16; ++r) { mxa = fmaxf(fmaxf(mxa, pp[0][r]), pp[1][r]); mxb = fmaxf(fmaxf(mxb, pp[2][r]), pp[3][r]); }
;             float mx = fmaxf(mxa, mxb);
;             mx = fmaxf(mx, shx(mx, 32, lane));
;             const bool first = (t == 0);
;             if (first || __any(mx > 8.f)) {
;                 const float d = first ? mx : fmaxf(mx, 0.f);
;                 m_run += d;
; #pragma unroll
;                 for (int j = 0; j < 4; ++j)
; #pragma unroll
;                     for (int r = 0; r < 16; ++r) pp[j][r] -= d;
; #pragma unroll
;                 for (int r = 0; r < 16; ++r) negm[r] = -m_run;
;                 if (!first) {
;                     const float alpha = __builtin_amdgcn_exp2f(-d); l_run *= alpha;
;                     if (hi == 0) wsf[r32] = alpha;
;                     LDS_WAIT();
; #pragma unroll
;                     for (int r = 0; r < 16; ++r) { const float f = wsf[crow(r, hi)]; o0[r] *= f; o1[r] *= f; }
;                     LDS_WAIT();
;                 }
;             }
	v_mfma_f32_32x32x16_bf16 v[64:79], v[232:235], v[124:127], v[64:79]
	s_waitcnt lgkmcnt(0)
	v_mfma_f32_32x32x16_bf16 v[48:63], v[242:245], v[124:127], v[48:63]
	s_nop 10
	v_max_f32_e32 v157, v64, v64
	v_max_f32_e32 v155, v48, v48
	v_max_f32_e32 v155, v157, v155
	v_max3_f32 v155, v155, v65, v49
	v_max3_f32 v155, v155, v66, v50
	v_max3_f32 v155, v155, v67, v51
	v_max3_f32 v155, v155, v68, v52
	v_max3_f32 v155, v155, v69, v53
	v_max3_f32 v157, v96, v80, v97
	v_max3_f32 v157, v157, v81, v98
	v_max3_f32 v157, v157, v82, v99
	v_max3_f32 v157, v157, v83, v100
	v_max3_f32 v157, v157, v84, v101
	v_max3_f32 v157, v157, v85, v102
	v_max3_f32 v155, v155, v70, v54
	v_max3_f32 v157, v157, v86, v103
	v_max3_f32 v155, v155, v71, v55
	v_max3_f32 v157, v157, v87, v104
	v_max3_f32 v155, v155, v72, v56
	v_max3_f32 v157, v157, v88, v105
	v_max3_f32 v155, v155, v73, v57
	v_max3_f32 v157, v157, v89, v106
	v_max3_f32 v155, v155, v74, v58
	v_max3_f32 v157, v157, v90, v107
	v_max3_f32 v155, v155, v75, v59
	v_max3_f32 v157, v157, v91, v108
	v_max3_f32 v155, v155, v76, v60
	v_max3_f32 v157, v157, v92, v109
	v_max3_f32 v155, v155, v77, v61
	v_max3_f32 v157, v157, v93, v110
	v_max3_f32 v155, v155, v78, v62
	v_max3_f32 v157, v157, v94, v111
	v_max3_f32 v155, v155, v79, v63
	v_max3_f32 v155, v157, v95, v155
	ds_bpermute_b32 v157, v209, v155
	s_waitcnt lgkmcnt(0)
	v_max_f32_e32 v157, v157, v157
	v_max_f32_e32 v155, v155, v157
	v_cmp_lt_f32_e32 vcc, s19, v155
	s_cbranch_vccz .LBB0_735
	v_max_f32_e32 v32, v155, v155
	v_max_f32_e32 v32, 0, v32
	v_exp_f32_e64 v33, -v32
	s_and_saveexec_b64 s[50:51], s[4:5]
	ds_write_b32 v219, v33
	s_or_b64 exec, exec, s[50:51]
	s_waitcnt lgkmcnt(0)
	v_pk_add_f32 v[96:97], v[96:97], v[32:33] op_sel_hi:[1,0] neg_lo:[0,1] neg_hi:[0,1]
	v_pk_add_f32 v[98:99], v[98:99], v[32:33] op_sel_hi:[1,0] neg_lo:[0,1] neg_hi:[0,1]
	v_pk_add_f32 v[100:101], v[100:101], v[32:33] op_sel_hi:[1,0] neg_lo:[0,1] neg_hi:[0,1]
	v_pk_add_f32 v[102:103], v[102:103], v[32:33] op_sel_hi:[1,0] neg_lo:[0,1] neg_hi:[0,1]
	v_pk_add_f32 v[104:105], v[104:105], v[32:33] op_sel_hi:[1,0] neg_lo:[0,1] neg_hi:[0,1]
	v_pk_add_f32 v[106:107], v[106:107], v[32:33] op_sel_hi:[1,0] neg_lo:[0,1] neg_hi:[0,1]
	v_pk_add_f32 v[108:109], v[108:109], v[32:33] op_sel_hi:[1,0] neg_lo:[0,1] neg_hi:[0,1]
	v_pk_add_f32 v[110:111], v[110:111], v[32:33] op_sel_hi:[1,0] neg_lo:[0,1] neg_hi:[0,1]
	v_pk_add_f32 v[80:81], v[80:81], v[32:33] op_sel_hi:[1,0] neg_lo:[0,1] neg_hi:[0,1]
	v_pk_add_f32 v[82:83], v[82:83], v[32:33] op_sel_hi:[1,0] neg_lo:[0,1] neg_hi:[0,1]
	v_pk_add_f32 v[84:85], v[84:85], v[32:33] op_sel_hi:[1,0] neg_lo:[0,1] neg_hi:[0,1]
	v_pk_add_f32 v[86:87], v[86:87], v[32:33] op_sel_hi:[1,0] neg_lo:[0,1] neg_hi:[0,1]
	v_pk_add_f32 v[88:89], v[88:89], v[32:33] op_sel_hi:[1,0] neg_lo:[0,1] neg_hi:[0,1]
	v_pk_add_f32 v[90:91], v[90:91], v[32:33] op_sel_hi:[1,0] neg_lo:[0,1] neg_hi:[0,1]
	v_pk_add_f32 v[92:93], v[92:93], v[32:33] op_sel_hi:[1,0] neg_lo:[0,1] neg_hi:[0,1]
	v_pk_add_f32 v[94:95], v[94:95], v[32:33] op_sel_hi:[1,0] neg_lo:[0,1] neg_hi:[0,1]
	v_pk_add_f32 v[64:65], v[64:65], v[32:33] op_sel_hi:[1,0] neg_lo:[0,1] neg_hi:[0,1]
	v_pk_add_f32 v[66:67], v[66:67], v[32:33] op_sel_hi:[1,0] neg_lo:[0,1] neg_hi:[0,1]
	v_pk_add_f32 v[68:69], v[68:69], v[32:33] op_sel_hi:[1,0] neg_lo:[0,1] neg_hi:[0,1]
	v_pk_add_f32 v[70:71], v[70:71], v[32:33] op_sel_hi:[1,0] neg_lo:[0,1] neg_hi:[0,1]
	v_pk_add_f32 v[72:73], v[72:73], v[32:33] op_sel_hi:[1,0] neg_lo:[0,1] neg_hi:[0,1]
	v_pk_add_f32 v[74:75], v[74:75], v[32:33] op_sel_hi:[1,0] neg_lo:[0,1] neg_hi:[0,1]
	v_pk_add_f32 v[76:77], v[76:77], v[32:33] op_sel_hi:[1,0] neg_lo:[0,1] neg_hi:[0,1]
	v_pk_add_f32 v[78:79], v[78:79], v[32:33] op_sel_hi:[1,0] neg_lo:[0,1] neg_hi:[0,1]
	v_pk_add_f32 v[48:49], v[48:49], v[32:33] op_sel_hi:[1,0] neg_lo:[0,1] neg_hi:[0,1]
	v_pk_add_f32 v[50:51], v[50:51], v[32:33] op_sel_hi:[1,0] neg_lo:[0,1] neg_hi:[0,1]
	v_pk_add_f32 v[52:53], v[52:53], v[32:33] op_sel_hi:[1,0] neg_lo:[0,1] neg_hi:[0,1]
	v_pk_add_f32 v[54:55], v[54:55], v[32:33] op_sel_hi:[1,0] neg_lo:[0,1] neg_hi:[0,1]
	v_pk_add_f32 v[56:57], v[56:57], v[32:33] op_sel_hi:[1,0] neg_lo:[0,1] neg_hi:[0,1]
	v_pk_add_f32 v[58:59], v[58:59], v[32:33] op_sel_hi:[1,0] neg_lo:[0,1] neg_hi:[0,1]
	v_pk_add_f32 v[60:61], v[60:61], v[32:33] op_sel_hi:[1,0] neg_lo:[0,1] neg_hi:[0,1]
	v_pk_add_f32 v[62:63], v[62:63], v[32:33] op_sel_hi:[1,0] neg_lo:[0,1] neg_hi:[0,1]
	v_pk_add_f32 v[196:197], v[194:195], v[32:33]
	v_pk_mul_f32 v[44:45], v[194:195], v[32:33]
	ds_read_b128 v[32:35], v222 offset:64
	ds_read_b128 v[36:39], v222 offset:96
	ds_read_b128 v[40:43], v222
	ds_read_b128 v[224:227], v222 offset:32
	v_mov_b32_e32 v197, v45
	s_waitcnt lgkmcnt(0)
	v_pk_add_f32 v[46:47], v[196:197], 0 neg_lo:[1,1] neg_hi:[1,1]
	s_waitcnt lgkmcnt(2)
	v_pk_mul_f32 v[12:13], v[12:13], v[36:37]
	v_pk_mul_f32 v[8:9], v[8:9], v[32:33]
	s_waitcnt lgkmcnt(0)
	v_pk_mul_f32 v[4:5], v[4:5], v[224:225]
	v_pk_mul_f32 v[14:15], v[14:15], v[38:39]
	v_pk_mul_f32 v[10:11], v[10:11], v[34:35]
	v_pk_mul_f32 v[6:7], v[6:7], v[226:227]
	v_pk_mul_f32 v[2:3], v[2:3], v[42:43]
	v_pk_mul_f32 v[0:1], v[0:1], v[40:41]
	v_pk_mul_f32 v[28:29], v[28:29], v[36:37]
	v_pk_mul_f32 v[24:25], v[24:25], v[32:33]
	v_pk_mul_f32 v[20:21], v[20:21], v[224:225]
	v_pk_mul_f32 v[30:31], v[30:31], v[38:39]
	v_pk_mul_f32 v[26:27], v[26:27], v[34:35]
	v_pk_mul_f32 v[22:23], v[22:23], v[226:227]
	v_pk_mul_f32 v[18:19], v[18:19], v[42:43]
	v_pk_mul_f32 v[16:17], v[16:17], v[40:41]
	v_mov_b32_e32 v47, v46
	v_mov_b32_e32 v45, v46
	v_mov_b32_e32 v44, v46
	v_mov_b32_e32 v43, v46
	v_mov_b32_e32 v42, v46
	v_mov_b32_e32 v41, v46
	v_mov_b32_e32 v40, v46
	v_mov_b32_e32 v39, v46
	v_mov_b32_e32 v38, v46
	v_mov_b32_e32 v37, v46
	v_mov_b32_e32 v36, v46
	v_mov_b32_e32 v35, v46
	v_mov_b32_e32 v34, v46
	v_mov_b32_e32 v33, v46
	v_mov_b32_e32 v32, v46
	v_mov_b64_e32 v[194:195], v[196:197]

; #define PG8_STAGE(bufoff, gbase, voff) do { _Pragma("unroll") for (int _i = 0; _i < 2; ++_i) \
;         __builtin_amdgcn_global_load_lds((const unsigned*)((const char*)(gbase) + (voff)[_i]), (LAS unsigned*)(lds + (bufoff) + ldsw + _i * 8192), 16, 0, 0); } while (0)
; #define PG8_WAIT_V(n) asm volatile("s_waitcnt vmcnt(" #n ")" ::: "memory")
; #define PG8_BAR __builtin_amdgcn_s_barrier()
; template <class Epi, class Addr>
; __device__ __forceinline__ void gemm_phase(LAS unsigned char* lds, const Gemm g, const StaticOrder& S, const Addr& AD, const Epi& E) {
;     ...
;     Unit cur, nxt; int ui = 0;
;     if (!S.next(0, cur)) return;
;     Acc acc;
; #pragma unroll
;     for (int a = 0; a < 2; ++a)
; #pragma unroll
;         for (int b = 0; b < 2; ++b)
; #pragma unroll
;             for (int m = 0; m < 4; ++m)
; #pragma unroll
;                 for (int n = 0; n < 2; ++n) acc[a][b][m][n] = (f32x4){0.f, 0.f, 0.f, 0.f};
;     bf16x8 At[4][2], B0[2][2], B1[2][2];
;     const char* cA; const char* cB; AD.get(g, cur, cA, cB);
;     PG8_STAGE(PG8_SB(0, 0), cB, voffB); PG8_STAGE(PG8_SB(0, 1), cB + hstepB, voffB); PG8_STAGE(PG8_SA(0, 0), cA, voffA); PG8_STAGE(PG8_SA(0, 1), cA + hstepA, voffA);
;     if (wr == 1) PG8_BAR;
;     PG8_WAIT_V(2); PG8_BAR;
;     PG8_STAGE(PG8_SB(1, 0), cB + kstep, voffB); PG8_STAGE(PG8_SA(1, 0), cA + kstep, voffA); PG8_STAGE(PG8_SB(1, 1), cB + hstepB + kstep, voffB);
;     PG8_WAIT_V(6); PG8_BAR;
;     for (;;) {
;         const bool has_next = S.next(ui + 1, nxt);
;         const char* nA = cA; const char* nB = cB; if (has_next) AD.get(g, nxt, nA, nB);
.LBB0_1254:
	s_ashr_i32 s57, s56, 31
	s_lshl_b64 s[58:59], s[56:57], 19
	s_add_u32 s58, s1, s58
	s_addc_u32 s59, s2, s59
	s_ashr_i32 s55, s54, 31
	s_lshl_b64 s[60:61], s[54:55], 19
	s_add_u32 s60, s3, s60
	v_mov_b32_e32 v127, 0
	s_addc_u32 s61, s14, s61
	s_andn2_b64 vcc, exec, s[50:51]
	v_mov_b32_e32 v126, v127
	v_mov_b32_e32 v125, v127
	v_mov_b32_e32 v124, v127
	v_mov_b32_e32 v119, v127
	v_mov_b32_e32 v118, v127
	v_mov_b32_e32 v117, v127
	v_mov_b32_e32 v116, v127
	v_mov_b32_e32 v111, v127
	v_mov_b32_e32 v110, v127
	v_mov_b32_e32 v109, v127
	v_mov_b32_e32 v108, v127
	v_mov_b32_e32 v103, v127
	v_mov_b32_e32 v102, v127
	v_mov_b32_e32 v101, v127
	v_mov_b32_e32 v100, v127
	v_mov_b32_e32 v95, v127
	v_mov_b32_e32 v94, v127
	v_mov_b32_e32 v93, v127
	v_mov_b32_e32 v92, v127
	v_mov_b32_e32 v87, v127
	v_mov_b32_e32 v86, v127
	v_mov_b32_e32 v85, v127
	v_mov_b32_e32 v84, v127
	v_mov_b32_e32 v79, v127
	v_mov_b32_e32 v78, v127
	v_mov_b32_e32 v77, v127
	v_mov_b32_e32 v76, v127
	v_mov_b32_e32 v71, v127
	v_mov_b32_e32 v70, v127
	v_mov_b32_e32 v69, v127
	v_mov_b32_e32 v68, v127
	v_mov_b32_e32 v123, v127
	v_mov_b32_e32 v122, v127
	v_mov_b32_e32 v121, v127
	v_mov_b32_e32 v120, v127
	v_mov_b32_e32 v115, v127
	v_mov_b32_e32 v114, v127
	v_mov_b32_e32 v113, v127
	v_mov_b32_e32 v112, v127
	v_mov_b32_e32 v107, v127
	v_mov_b32_e32 v106, v127
	v_mov_b32_e32 v105, v127
	v_mov_b32_e32 v104, v127
	v_mov_b32_e32 v99, v127
	v_mov_b32_e32 v98, v127
	v_mov_b32_e32 v97, v127
	v_mov_b32_e32 v96, v127
	v_mov_b32_e32 v91, v127
	v_mov_b32_e32 v90, v127
	v_mov_b32_e32 v89, v127
	v_mov_b32_e32 v88, v127
	v_mov_b32_e32 v83, v127
	v_mov_b32_e32 v82, v127
	v_mov_b32_e32 v81, v127
	v_mov_b32_e32 v80, v127
	v_mov_b32_e32 v75, v127
	v_mov_b32_e32 v74, v127
	v_mov_b32_e32 v73, v127
	v_mov_b32_e32 v72, v127
	v_mov_b32_e32 v67, v127
	v_mov_b32_e32 v66, v127
	v_mov_b32_e32 v65, v127
	v_mov_b32_e32 v64, v127
	v_mov_b32_e32 v63, v127
	v_mov_b32_e32 v62, v127
	v_mov_b32_e32 v61, v127
	v_mov_b32_e32 v60, v127
	v_mov_b32_e32 v55, v127
	v_mov_b32_e32 v54, v127
	v_mov_b32_e32 v53, v127
	v_mov_b32_e32 v52, v127
	v_mov_b32_e32 v47, v127
	v_mov_b32_e32 v46, v127
	v_mov_b32_e32 v45, v127
	v_mov_b32_e32 v44, v127
	v_mov_b32_e32 v39, v127
	v_mov_b32_e32 v38, v127
	v_mov_b32_e32 v37, v127
	v_mov_b32_e32 v36, v127
	v_mov_b32_e32 v31, v127
	v_mov_b32_e32 v30, v127
	v_mov_b32_e32 v29, v127
	v_mov_b32_e32 v28, v127
	v_mov_b32_e32 v23, v127
	v_mov_b32_e32 v22, v127
	v_mov_b32_e32 v21, v127
	v_mov_b32_e32 v20, v127
	v_mov_b32_e32 v15, v127
	v_mov_b32_e32 v14, v127
	v_mov_b32_e32 v13, v127
	v_mov_b32_e32 v12, v127
	v_mov_b32_e32 v7, v127
	v_mov_b32_e32 v6, v127
	v_mov_b32_e32 v5, v127
	v_mov_b32_e32 v4, v127
	v_mov_b32_e32 v59, v127
	v_mov_b32_e32 v58, v127
	v_mov_b32_e32 v57, v127
	v_mov_b32_e32 v56, v127
	v_mov_b32_e32 v51, v127
	v_mov_b32_e32 v50, v127
	v_mov_b32_e32 v49, v127
	v_mov_b32_e32 v48, v127
	v_mov_b32_e32 v43, v127
	v_mov_b32_e32 v42, v127
	v_mov_b32_e32 v41, v127
	v_mov_b32_e32 v40, v127
	v_mov_b32_e32 v35, v127
	v_mov_b32_e32 v34, v127
	v_mov_b32_e32 v33, v127
	v_mov_b32_e32 v32, v127
	v_mov_b32_e32 v27, v127
	v_mov_b32_e32 v26, v127
	v_mov_b32_e32 v25, v127
	v_mov_b32_e32 v24, v127
	v_mov_b32_e32 v19, v127
	v_mov_b32_e32 v18, v127
	v_mov_b32_e32 v17, v127
	v_mov_b32_e32 v16, v127
	v_mov_b32_e32 v11, v127
	v_mov_b32_e32 v10, v127
	v_mov_b32_e32 v9, v127
	v_mov_b32_e32 v8, v127
	v_mov_b32_e32 v3, v127
	v_mov_b32_e32 v2, v127
	v_mov_b32_e32 v1, v127
	v_mov_b32_e32 v0, v127
	s_cbranch_vccnz .LBB0_1257
	s_and_b64 s[66:67], s[4:5], exec
	s_cselect_b32 s55, s59, s63
	s_cselect_b32 s57, s58, s62
	s_cselect_b32 s72, s61, s65
	s_cselect_b32 s73, s60, s64
	s_add_u32 s62, s62, 0x40080
	s_addc_u32 s63, s63, 0
	s_add_u32 s74, s64, 0x100
	v_mov_b32_e32 v0, 0
	s_addc_u32 s75, s65, 0
	s_mov_b32 s64, 0
	v_mov_b32_e32 v1, v0
	v_mov_b32_e32 v2, v0
	v_mov_b32_e32 v3, v0
	v_mov_b32_e32 v8, v0
	v_mov_b32_e32 v9, v0
	v_mov_b32_e32 v10, v0
	v_mov_b32_e32 v11, v0
	v_mov_b32_e32 v16, v0
	v_mov_b32_e32 v17, v0
	v_mov_b32_e32 v18, v0
	v_mov_b32_e32 v19, v0
	v_mov_b32_e32 v24, v0
	v_mov_b32_e32 v25, v0
	v_mov_b32_e32 v26, v0
	v_mov_b32_e32 v27, v0
	v_mov_b32_e32 v32, v0
	v_mov_b32_e32 v33, v0
	v_mov_b32_e32 v34, v0
	v_mov_b32_e32 v35, v0
	v_mov_b32_e32 v40, v0
	v_mov_b32_e32 v41, v0
	v_mov_b32_e32 v42, v0
	v_mov_b32_e32 v43, v0
	v_mov_b32_e32 v48, v0
	v_mov_b32_e32 v49, v0
	v_mov_b32_e32 v50, v0
	v_mov_b32_e32 v51, v0
	v_mov_b32_e32 v56, v0
	v_mov_b32_e32 v57, v0
	v_mov_b32_e32 v58, v0
	v_mov_b32_e32 v59, v0
	v_mov_b32_e32 v4, v0
	v_mov_b32_e32 v5, v0
	v_mov_b32_e32 v6, v0
	v_mov_b32_e32 v7, v0
	v_mov_b32_e32 v12, v0
	v_mov_b32_e32 v13, v0
	v_mov_b32_e32 v14, v0
	v_mov_b32_e32 v15, v0
	v_mov_b32_e32 v20, v0
	v_mov_b32_e32 v21, v0
	v_mov_b32_e32 v22, v0
	v_mov_b32_e32 v23, v0
	v_mov_b32_e32 v28, v0
	v_mov_b32_e32 v29, v0
	v_mov_b32_e32 v30, v0
	v_mov_b32_e32 v31, v0
	v_mov_b32_e32 v36, v0
	v_mov_b32_e32 v37, v0
	v_mov_b32_e32 v38, v0
	v_mov_b32_e32 v39, v0
	v_mov_b32_e32 v44, v0
	v_mov_b32_e32 v45, v0
	v_mov_b32_e32 v46, v0
	v_mov_b32_e32 v47, v0
	v_mov_b32_e32 v52, v0
	v_mov_b32_e32 v53, v0
	v_mov_b32_e32 v54, v0
	v_mov_b32_e32 v55, v0
	v_mov_b32_e32 v60, v0
	v_mov_b32_e32 v61, v0
	v_mov_b32_e32 v62, v0
	v_mov_b32_e32 v63, v0
	v_mov_b32_e32 v64, v0
	v_mov_b32_e32 v65, v0
	v_mov_b32_e32 v66, v0
	v_mov_b32_e32 v67, v0
	v_mov_b32_e32 v72, v0
	v_mov_b32_e32 v73, v0
	v_mov_b32_e32 v74, v0
	v_mov_b32_e32 v75, v0
	v_mov_b32_e32 v80, v0
	v_mov_b32_e32 v81, v0
	v_mov_b32_e32 v82, v0
	v_mov_b32_e32 v83, v0
	v_mov_b32_e32 v88, v0
	v_mov_b32_e32 v89, v0
	v_mov_b32_e32 v90, v0
	v_mov_b32_e32 v91, v0
	v_mov_b32_e32 v96, v0
	v_mov_b32_e32 v97, v0
	v_mov_b32_e32 v98, v0
	v_mov_b32_e32 v99, v0
	v_mov_b32_e32 v104, v0
	v_mov_b32_e32 v105, v0
	v_mov_b32_e32 v106, v0
	v_mov_b32_e32 v107, v0
	v_mov_b32_e32 v112, v0
	v_mov_b32_e32 v113, v0
	v_mov_b32_e32 v114, v0
	v_mov_b32_e32 v115, v0
	v_mov_b32_e32 v120, v0
	v_mov_b32_e32 v121, v0
	v_mov_b32_e32 v122, v0
	v_mov_b32_e32 v123, v0
	v_mov_b32_e32 v68, v0
	v_mov_b32_e32 v69, v0
	v_mov_b32_e32 v70, v0
	v_mov_b32_e32 v71, v0
	v_mov_b32_e32 v76, v0
	v_mov_b32_e32 v77, v0
	v_mov_b32_e32 v78, v0
	v_mov_b32_e32 v79, v0
	v_mov_b32_e32 v84, v0
	v_mov_b32_e32 v85, v0
	v_mov_b32_e32 v86, v0
	v_mov_b32_e32 v87, v0
	v_mov_b32_e32 v92, v0
	v_mov_b32_e32 v93, v0
	v_mov_b32_e32 v94, v0
	v_mov_b32_e32 v95, v0
	v_mov_b32_e32 v100, v0
	v_mov_b32_e32 v101, v0
	v_mov_b32_e32 v102, v0
	v_mov_b32_e32 v103, v0
	v_mov_b32_e32 v108, v0
	v_mov_b32_e32 v109, v0
	v_mov_b32_e32 v110, v0
	v_mov_b32_e32 v111, v0
	v_mov_b32_e32 v116, v0
	v_mov_b32_e32 v117, v0
	v_mov_b32_e32 v118, v0
	v_mov_b32_e32 v119, v0
	v_mov_b32_e32 v124, v0
	v_mov_b32_e32 v125, v0
	v_mov_b32_e32 v126, v0
	v_mov_b32_e32 v127, v0
	v_add_u32_e32 v178, 0x10000, v186
	v_add_u32_e32 v179, 0x18000, v186
; #define PG8_STAGE(bufoff, gbase, voff) do { _Pragma("unroll") for (int _i = 0; _i < 2; ++_i) \
;         __builtin_amdgcn_global_load_lds((const unsigned*)((const char*)(gbase) + (voff)[_i]), (LAS unsigned*)(lds + (bufoff) + ldsw + _i * 8192), 16, 0, 0); } while (0)
; #define PG8_LDA(dst, b, h) do { _Pragma("unroll") for (int m = 0; m < 4; ++m) _Pragma("unroll") for (int k = 0; k < 2; ++k) dst[m][k] = *(const LAS bf16x8*)(lds + PG8_SA(b, h) + aoff + m * 2048 + k * 1024); } while (0)
; #define PG8_LDB(dst, b, h) do { _Pragma("unroll") for (int n = 0; n < 2; ++n) _Pragma("unroll") for (int k = 0; k < 2; ++k) dst[n][k] = *(const LAS bf16x8*)(lds + PG8_SB(b, h) + boff + n * 2048 + k * 1024); } while (0)
; #define PG8_MMA(ai, bj, At, Bt) do { __builtin_amdgcn_s_setprio(1); _Pragma("unroll") for (int m = 0; m < 4; ++m) _Pragma("unroll") for (int n = 0; n < 2; ++n) _Pragma("unroll") for (int k = 0; k < 2; ++k) \
;         acc[ai][bj][m][n] = __builtin_amdgcn_mfma_f32_16x16x32_bf16(Bt[n][k], At[m][k], acc[ai][bj][m][n], 0, 0, 0); __builtin_amdgcn_s_setprio(0); } while (0)
; #define PG8_WAIT_V(n) asm volatile("s_waitcnt vmcnt(" #n ")" ::: "memory")
; #define PG8_WAIT_L(n) asm volatile("s_waitcnt lgkmcnt(" #n ")" ::: "memory")
; #define PG8_BAR __builtin_amdgcn_s_barrier()
; #define PG8_SCHED __builtin_amdgcn_sched_barrier(0)
; template <class Epi, class Addr>
; __device__ __forceinline__ void gemm_phase(LAS unsigned char* lds, const Gemm g, const StaticOrder& S, const Addr& AD, const Epi& E) {
;     ...
;             PG8_LDB(B0, 0, 0); PG8_LDB(B1, 0, 1); PG8_SCHED; PG8_LDA(At, 0, 0); PG8_STAGE(PG8_SA(1, 1), a1 + hstepA, voffA);
;             PG8_WAIT_V(8); PG8_WAIT_L(0); PG8_BAR; PG8_MMA(0, 0, At, B0); PG8_MMA(0, 1, At, B1); PG8_BAR; PG8_SCHED;
;             PG8_LDA(At, 0, 1); PG8_STAGE(PG8_SB(0, 0), b2, voffB); PG8_STAGE(PG8_SB(0, 1), b2 + hstepB, voffB); PG8_STAGE(PG8_SA(0, 0), a2, voffA);
;             PG8_WAIT_V(8); PG8_WAIT_L(0); PG8_BAR; PG8_MMA(1, 0, At, B0); PG8_MMA(1, 1, At, B1); PG8_BAR; PG8_SCHED;
.LBB0_1256:
	s_add_i32 s76, s64, 2
	s_add_u32 s24, s62, 0xfffc0080
	s_addc_u32 s25, s63, -1
	s_add_i32 s28, 0, 0x10000
	s_cmp_eq_u32 s70, s64
	s_cselect_b32 s67, s55, s25
	s_cselect_b32 s66, s57, s24
	s_cselect_b32 s65, s72, s75
	s_cselect_b32 s64, s73, s74
	s_add_i32 s24, 0, 0x14000
	ds_read_b128 v[128:131], v178
	ds_read_b128 v[132:135], v178 offset:1024
	ds_read_b128 v[136:139], v178 offset:2048
	ds_read_b128 v[140:143], v178 offset:3072
	ds_read_b128 v[144:147], v178 offset:16384
	ds_read_b128 v[148:151], v178 offset:17408
	ds_read_b128 v[162:165], v178 offset:18432
	ds_read_b128 v[166:169], v178 offset:19456
	s_add_i32 m0, s17, 0xc000
	ds_read_b128 v[170:173], v187
	ds_read_b128 v[174:177], v187 offset:1024
	ds_read_b128 v[188:191], v187 offset:2048
	ds_read_b128 v[192:195], v187 offset:3072
	ds_read_b128 v[196:199], v187 offset:4096
	ds_read_b128 v[222:225], v187 offset:5120
	ds_read_b128 v[226:229], v187 offset:6144
	ds_read_b128 v[230:233], v187 offset:7168
	global_load_lds_dwordx4 v158, s[62:63]
	s_add_i32 m0, s17, 0xe000
	s_nop 0
	global_load_lds_dwordx4 v160, s[62:63]
	s_waitcnt vmcnt(8)
	s_waitcnt lgkmcnt(0)
	s_barrier
	s_setprio 1
	s_waitcnt lgkmcnt(0)
	v_mfma_f32_16x16x32_bf16 v[124:127], v[128:131], v[170:173], v[124:127]
	v_mfma_f32_16x16x32_bf16 v[116:119], v[136:139], v[170:173], v[116:119]
	v_mfma_f32_16x16x32_bf16 v[108:111], v[128:131], v[188:191], v[108:111]
	v_mfma_f32_16x16x32_bf16 v[100:103], v[136:139], v[188:191], v[100:103]
	v_mfma_f32_16x16x32_bf16 v[92:95], v[128:131], v[196:199], v[92:95]
	v_mfma_f32_16x16x32_bf16 v[84:87], v[136:139], v[196:199], v[84:87]
	v_mfma_f32_16x16x32_bf16 v[76:79], v[128:131], v[226:229], v[76:79]
	v_mfma_f32_16x16x32_bf16 v[68:71], v[136:139], v[226:229], v[68:71]
	v_mfma_f32_16x16x32_bf16 v[124:127], v[132:135], v[174:177], v[124:127]
	v_mfma_f32_16x16x32_bf16 v[116:119], v[140:143], v[174:177], v[116:119]
	v_mfma_f32_16x16x32_bf16 v[108:111], v[132:135], v[192:195], v[108:111]
	v_mfma_f32_16x16x32_bf16 v[100:103], v[140:143], v[192:195], v[100:103]
	v_mfma_f32_16x16x32_bf16 v[92:95], v[132:135], v[222:225], v[92:95]
	v_mfma_f32_16x16x32_bf16 v[84:87], v[140:143], v[222:225], v[84:87]
	v_mfma_f32_16x16x32_bf16 v[76:79], v[132:135], v[230:233], v[76:79]
	v_mfma_f32_16x16x32_bf16 v[68:71], v[140:143], v[230:233], v[68:71]
	s_setprio 0
	s_setprio 1
	v_mfma_f32_16x16x32_bf16 v[120:123], v[144:147], v[170:173], v[120:123]
	v_mfma_f32_16x16x32_bf16 v[112:115], v[162:165], v[170:173], v[112:115]
	v_mfma_f32_16x16x32_bf16 v[104:107], v[144:147], v[188:191], v[104:107]
	v_mfma_f32_16x16x32_bf16 v[96:99], v[162:165], v[188:191], v[96:99]
	v_mfma_f32_16x16x32_bf16 v[88:91], v[144:147], v[196:199], v[88:91]
	v_mfma_f32_16x16x32_bf16 v[80:83], v[162:165], v[196:199], v[80:83]
	v_mfma_f32_16x16x32_bf16 v[72:75], v[144:147], v[226:229], v[72:75]
	v_mfma_f32_16x16x32_bf16 v[64:67], v[162:165], v[226:229], v[64:67]
	v_mfma_f32_16x16x32_bf16 v[120:123], v[148:151], v[174:177], v[120:123]
	v_mfma_f32_16x16x32_bf16 v[112:115], v[166:169], v[174:177], v[112:115]
	v_mfma_f32_16x16x32_bf16 v[104:107], v[148:151], v[192:195], v[104:107]
	v_mfma_f32_16x16x32_bf16 v[96:99], v[166:169], v[192:195], v[96:99]
	v_mfma_f32_16x16x32_bf16 v[88:91], v[148:151], v[222:225], v[88:91]
	v_mfma_f32_16x16x32_bf16 v[80:83], v[166:169], v[222:225], v[80:83]
	v_mfma_f32_16x16x32_bf16 v[72:75], v[148:151], v[230:233], v[72:75]
	v_mfma_f32_16x16x32_bf16 v[64:67], v[166:169], v[230:233], v[64:67]
	s_setprio 0
	s_barrier
	s_add_i32 s25, s28, s15
	s_mov_b32 m0, s25
	ds_read_b128 v[170:173], v187 offset:16384
	ds_read_b128 v[174:177], v187 offset:17408
	ds_read_b128 v[188:191], v187 offset:18432
	ds_read_b128 v[192:195], v187 offset:19456
	ds_read_b128 v[196:199], v187 offset:20480
	ds_read_b128 v[222:225], v187 offset:21504
	ds_read_b128 v[226:229], v187 offset:22528
	ds_read_b128 v[230:233], v187 offset:23552
	global_load_lds_dwordx4 v200, s[64:65]
	s_add_i32 m0, s25, 0x2000
	s_add_u32 s78, s64, 0x40000
	s_addc_u32 s79, s65, 0
	s_add_i32 s24, s24, s15
	global_load_lds_dwordx4 v152, s[64:65]
	s_mov_b32 m0, s24
	s_nop 0
	global_load_lds_dwordx4 v200, s[78:79]
	s_add_i32 m0, s24, 0x2000
	s_nop 0
	global_load_lds_dwordx4 v152, s[78:79]
	s_mov_b32 m0, s17
	s_nop 0
	global_load_lds_dwordx4 v156, s[66:67]
	s_mov_b32 m0, s18
	s_nop 0
	global_load_lds_dwordx4 v154, s[66:67]
	s_waitcnt vmcnt(8)
	s_waitcnt lgkmcnt(0)
	s_barrier
	s_setprio 1
	s_waitcnt lgkmcnt(0)
	v_mfma_f32_16x16x32_bf16 v[60:63], v[128:131], v[170:173], v[60:63]
	v_mfma_f32_16x16x32_bf16 v[52:55], v[136:139], v[170:173], v[52:55]
	v_mfma_f32_16x16x32_bf16 v[44:47], v[128:131], v[188:191], v[44:47]
	v_mfma_f32_16x16x32_bf16 v[36:39], v[136:139], v[188:191], v[36:39]
	v_mfma_f32_16x16x32_bf16 v[28:31], v[128:131], v[196:199], v[28:31]
	v_mfma_f32_16x16x32_bf16 v[20:23], v[136:139], v[196:199], v[20:23]
	v_mfma_f32_16x16x32_bf16 v[12:15], v[128:131], v[226:229], v[12:15]
	v_mfma_f32_16x16x32_bf16 v[4:7], v[136:139], v[226:229], v[4:7]
	v_mfma_f32_16x16x32_bf16 v[60:63], v[132:135], v[174:177], v[60:63]
	v_mfma_f32_16x16x32_bf16 v[52:55], v[140:143], v[174:177], v[52:55]
	v_mfma_f32_16x16x32_bf16 v[44:47], v[132:135], v[192:195], v[44:47]
	v_mfma_f32_16x16x32_bf16 v[36:39], v[140:143], v[192:195], v[36:39]
	v_mfma_f32_16x16x32_bf16 v[28:31], v[132:135], v[222:225], v[28:31]
	v_mfma_f32_16x16x32_bf16 v[20:23], v[140:143], v[222:225], v[20:23]
	v_mfma_f32_16x16x32_bf16 v[12:15], v[132:135], v[230:233], v[12:15]
	v_mfma_f32_16x16x32_bf16 v[4:7], v[140:143], v[230:233], v[4:7]
	s_setprio 0
	s_setprio 1
	v_mfma_f32_16x16x32_bf16 v[56:59], v[144:147], v[170:173], v[56:59]
	v_mfma_f32_16x16x32_bf16 v[48:51], v[162:165], v[170:173], v[48:51]
	v_mfma_f32_16x16x32_bf16 v[40:43], v[144:147], v[188:191], v[40:43]
	v_mfma_f32_16x16x32_bf16 v[32:35], v[162:165], v[188:191], v[32:35]
	v_mfma_f32_16x16x32_bf16 v[24:27], v[144:147], v[196:199], v[24:27]
	v_mfma_f32_16x16x32_bf16 v[16:19], v[162:165], v[196:199], v[16:19]
	v_mfma_f32_16x16x32_bf16 v[8:11], v[144:147], v[226:229], v[8:11]
	v_mfma_f32_16x16x32_bf16 v[0:3], v[162:165], v[226:229], v[0:3]
	v_mfma_f32_16x16x32_bf16 v[56:59], v[148:151], v[174:177], v[56:59]
	v_mfma_f32_16x16x32_bf16 v[48:51], v[166:169], v[174:177], v[48:51]
	v_mfma_f32_16x16x32_bf16 v[40:43], v[148:151], v[192:195], v[40:43]
	v_mfma_f32_16x16x32_bf16 v[32:35], v[166:169], v[192:195], v[32:35]
	v_mfma_f32_16x16x32_bf16 v[24:27], v[148:151], v[222:225], v[24:27]
	v_mfma_f32_16x16x32_bf16 v[16:19], v[166:169], v[222:225], v[16:19]
	v_mfma_f32_16x16x32_bf16 v[8:11], v[148:151], v[230:233], v[8:11]
	v_mfma_f32_16x16x32_bf16 v[0:3], v[166:169], v[230:233], v[0:3]
	s_setprio 0
	s_barrier
; #define PG8_STAGE(bufoff, gbase, voff) do { _Pragma("unroll") for (int _i = 0; _i < 2; ++_i) \
;         __builtin_amdgcn_global_load_lds((const unsigned*)((const char*)(gbase) + (voff)[_i]), (LAS unsigned*)(lds + (bufoff) + ldsw + _i * 8192), 16, 0, 0); } while (0)
; #define PG8_LDA(dst, b, h) do { _Pragma("unroll") for (int m = 0; m < 4; ++m) _Pragma("unroll") for (int k = 0; k < 2; ++k) dst[m][k] = *(const LAS bf16x8*)(lds + PG8_SA(b, h) + aoff + m * 2048 + k * 1024); } while (0)
; #define PG8_LDB(dst, b, h) do { _Pragma("unroll") for (int n = 0; n < 2; ++n) _Pragma("unroll") for (int k = 0; k < 2; ++k) dst[n][k] = *(const LAS bf16x8*)(lds + PG8_SB(b, h) + boff + n * 2048 + k * 1024); } while (0)
; #define PG8_MMA(ai, bj, At, Bt) do { __builtin_amdgcn_s_setprio(1); _Pragma("unroll") for (int m = 0; m < 4; ++m) _Pragma("unroll") for (int n = 0; n < 2; ++n) _Pragma("unroll") for (int k = 0; k < 2; ++k) \
;         acc[ai][bj][m][n] = __builtin_amdgcn_mfma_f32_16x16x32_bf16(Bt[n][k], At[m][k], acc[ai][bj][m][n], 0, 0, 0); __builtin_amdgcn_s_setprio(0); } while (0)
; #define PG8_WAIT_V(n) asm volatile("s_waitcnt vmcnt(" #n ")" ::: "memory")
; #define PG8_WAIT_L(n) asm volatile("s_waitcnt lgkmcnt(" #n ")" ::: "memory")
; #define PG8_BAR __builtin_amdgcn_s_barrier()
; #define PG8_SCHED __builtin_amdgcn_sched_barrier(0)
; template <class Epi, class Addr>
; __device__ __forceinline__ void gemm_phase(LAS unsigned char* lds, const Gemm g, const StaticOrder& S, const Addr& AD, const Epi& E) {
;     ...
;             PG8_LDB(B0, 1, 0); PG8_LDB(B1, 1, 1); PG8_SCHED; PG8_LDA(At, 1, 0); PG8_STAGE(PG8_SA(0, 1), a2 + hstepA, voffA);
;             PG8_WAIT_V(8); PG8_WAIT_L(0); PG8_BAR; PG8_MMA(0, 0, At, B0); PG8_MMA(0, 1, At, B1); PG8_BAR; PG8_SCHED;
;             PG8_LDA(At, 1, 1); PG8_STAGE(PG8_SB(1, 0), b3, voffB); PG8_STAGE(PG8_SB(1, 1), b3 + hstepB, voffB); PG8_STAGE(PG8_SA(1, 0), a3, voffA);
;             PG8_WAIT_V(8); PG8_WAIT_L(0); PG8_BAR; PG8_MMA(1, 0, At, B0); PG8_MMA(1, 1, At, B1); PG8_BAR; PG8_SCHED;
;         }
	s_add_i32 s24, 0, 0x18000
	s_add_i32 s25, 0, 0x1c000
	ds_read_b128 v[128:131], v179
	ds_read_b128 v[132:135], v179 offset:1024
	ds_read_b128 v[136:139], v179 offset:2048
	ds_read_b128 v[140:143], v179 offset:3072
	ds_read_b128 v[144:147], v179 offset:16384
	ds_read_b128 v[148:151], v179 offset:17408
	ds_read_b128 v[162:165], v179 offset:18432
	ds_read_b128 v[166:169], v179 offset:19456
	s_add_u32 s66, s66, 0x40000
	s_addc_u32 s67, s67, 0
	s_mov_b32 m0, s19
	ds_read_b128 v[170:173], v187 offset:32768
	ds_read_b128 v[174:177], v187 offset:33792
	ds_read_b128 v[188:191], v187 offset:34816
	ds_read_b128 v[192:195], v187 offset:35840
	ds_read_b128 v[196:199], v187 offset:36864
	ds_read_b128 v[222:225], v187 offset:37888
	ds_read_b128 v[226:229], v187 offset:38912
	ds_read_b128 v[230:233], v187 offset:39936
	global_load_lds_dwordx4 v156, s[66:67]
	s_mov_b32 m0, s20
	s_nop 0
	global_load_lds_dwordx4 v154, s[66:67]
	s_waitcnt vmcnt(8)
	s_waitcnt lgkmcnt(0)
	s_barrier
	s_setprio 1
	s_waitcnt lgkmcnt(0)
	v_mfma_f32_16x16x32_bf16 v[124:127], v[128:131], v[170:173], v[124:127]
	v_mfma_f32_16x16x32_bf16 v[116:119], v[136:139], v[170:173], v[116:119]
	v_mfma_f32_16x16x32_bf16 v[108:111], v[128:131], v[188:191], v[108:111]
	v_mfma_f32_16x16x32_bf16 v[100:103], v[136:139], v[188:191], v[100:103]
	v_mfma_f32_16x16x32_bf16 v[92:95], v[128:131], v[196:199], v[92:95]
	v_mfma_f32_16x16x32_bf16 v[84:87], v[136:139], v[196:199], v[84:87]
	v_mfma_f32_16x16x32_bf16 v[76:79], v[128:131], v[226:229], v[76:79]
	v_mfma_f32_16x16x32_bf16 v[68:71], v[136:139], v[226:229], v[68:71]
	v_mfma_f32_16x16x32_bf16 v[124:127], v[132:135], v[174:177], v[124:127]
	v_mfma_f32_16x16x32_bf16 v[116:119], v[140:143], v[174:177], v[116:119]
	v_mfma_f32_16x16x32_bf16 v[108:111], v[132:135], v[192:195], v[108:111]
	v_mfma_f32_16x16x32_bf16 v[100:103], v[140:143], v[192:195], v[100:103]
	v_mfma_f32_16x16x32_bf16 v[92:95], v[132:135], v[222:225], v[92:95]
	v_mfma_f32_16x16x32_bf16 v[84:87], v[140:143], v[222:225], v[84:87]
	v_mfma_f32_16x16x32_bf16 v[76:79], v[132:135], v[230:233], v[76:79]
	v_mfma_f32_16x16x32_bf16 v[68:71], v[140:143], v[230:233], v[68:71]
	s_setprio 0
	s_setprio 1
	v_mfma_f32_16x16x32_bf16 v[120:123], v[144:147], v[170:173], v[120:123]
	v_mfma_f32_16x16x32_bf16 v[112:115], v[162:165], v[170:173], v[112:115]
	v_mfma_f32_16x16x32_bf16 v[104:107], v[144:147], v[188:191], v[104:107]
	v_mfma_f32_16x16x32_bf16 v[96:99], v[162:165], v[188:191], v[96:99]
	v_mfma_f32_16x16x32_bf16 v[88:91], v[144:147], v[196:199], v[88:91]
	v_mfma_f32_16x16x32_bf16 v[80:83], v[162:165], v[196:199], v[80:83]
	v_mfma_f32_16x16x32_bf16 v[72:75], v[144:147], v[226:229], v[72:75]
	v_mfma_f32_16x16x32_bf16 v[64:67], v[162:165], v[226:229], v[64:67]
	v_mfma_f32_16x16x32_bf16 v[120:123], v[148:151], v[174:177], v[120:123]
	v_mfma_f32_16x16x32_bf16 v[112:115], v[166:169], v[174:177], v[112:115]
	v_mfma_f32_16x16x32_bf16 v[104:107], v[148:151], v[192:195], v[104:107]
	v_mfma_f32_16x16x32_bf16 v[96:99], v[166:169], v[192:195], v[96:99]
	v_mfma_f32_16x16x32_bf16 v[88:91], v[148:151], v[222:225], v[88:91]
	v_mfma_f32_16x16x32_bf16 v[80:83], v[166:169], v[222:225], v[80:83]
	v_mfma_f32_16x16x32_bf16 v[72:75], v[148:151], v[230:233], v[72:75]
	v_mfma_f32_16x16x32_bf16 v[64:67], v[166:169], v[230:233], v[64:67]
	s_setprio 0
	s_barrier
	s_add_i32 s24, s24, s15
	s_add_u32 s78, s64, s42
	s_addc_u32 s79, s65, s43
	s_mov_b32 m0, s24
	ds_read_b128 v[170:173], v187 offset:49152
	ds_read_b128 v[174:177], v187 offset:50176
	ds_read_b128 v[188:191], v187 offset:51200
	ds_read_b128 v[192:195], v187 offset:52224
	ds_read_b128 v[196:199], v187 offset:53248
	ds_read_b128 v[222:225], v187 offset:54272
	ds_read_b128 v[226:229], v187 offset:55296
	ds_read_b128 v[230:233], v187 offset:56320
	global_load_lds_dwordx4 v200, s[78:79]
	s_add_i32 m0, s24, 0x2000
	s_add_u32 s64, s64, 0x40080
	s_addc_u32 s65, s65, 0
	s_add_i32 s24, s25, s15
	global_load_lds_dwordx4 v152, s[78:79]
	s_mov_b32 m0, s24
	s_add_u32 s78, s66, s42
	s_addc_u32 s79, s67, s43
	global_load_lds_dwordx4 v200, s[64:65]
	s_add_i32 m0, s24, 0x2000
	s_sub_u32 s78, s78, 0x40000
	s_subb_u32 s79, s79, 0
	global_load_lds_dwordx4 v152, s[64:65]
	s_mov_b32 m0, s68
	s_nop 0
	global_load_lds_dwordx4 v156, s[78:79]
	s_mov_b32 m0, s69
	s_nop 0
	global_load_lds_dwordx4 v154, s[78:79]
	s_waitcnt vmcnt(8)
	s_waitcnt lgkmcnt(0)
	s_barrier
	s_setprio 1
	s_waitcnt lgkmcnt(0)
	v_mfma_f32_16x16x32_bf16 v[60:63], v[128:131], v[170:173], v[60:63]
	v_mfma_f32_16x16x32_bf16 v[52:55], v[136:139], v[170:173], v[52:55]
	v_mfma_f32_16x16x32_bf16 v[44:47], v[128:131], v[188:191], v[44:47]
	v_mfma_f32_16x16x32_bf16 v[36:39], v[136:139], v[188:191], v[36:39]
	v_mfma_f32_16x16x32_bf16 v[28:31], v[128:131], v[196:199], v[28:31]
	v_mfma_f32_16x16x32_bf16 v[20:23], v[136:139], v[196:199], v[20:23]
	v_mfma_f32_16x16x32_bf16 v[12:15], v[128:131], v[226:229], v[12:15]
	v_mfma_f32_16x16x32_bf16 v[4:7], v[136:139], v[226:229], v[4:7]
	v_mfma_f32_16x16x32_bf16 v[60:63], v[132:135], v[174:177], v[60:63]
	v_mfma_f32_16x16x32_bf16 v[52:55], v[140:143], v[174:177], v[52:55]
	v_mfma_f32_16x16x32_bf16 v[44:47], v[132:135], v[192:195], v[44:47]
	v_mfma_f32_16x16x32_bf16 v[36:39], v[140:143], v[192:195], v[36:39]
	v_mfma_f32_16x16x32_bf16 v[28:31], v[132:135], v[222:225], v[28:31]
	v_mfma_f32_16x16x32_bf16 v[20:23], v[140:143], v[222:225], v[20:23]
	v_mfma_f32_16x16x32_bf16 v[12:15], v[132:135], v[230:233], v[12:15]
	v_mfma_f32_16x16x32_bf16 v[4:7], v[140:143], v[230:233], v[4:7]
	s_setprio 0
	s_setprio 1
	v_mfma_f32_16x16x32_bf16 v[56:59], v[144:147], v[170:173], v[56:59]
	v_mfma_f32_16x16x32_bf16 v[48:51], v[162:165], v[170:173], v[48:51]
	v_mfma_f32_16x16x32_bf16 v[40:43], v[144:147], v[188:191], v[40:43]
	v_mfma_f32_16x16x32_bf16 v[32:35], v[162:165], v[188:191], v[32:35]
	v_mfma_f32_16x16x32_bf16 v[24:27], v[144:147], v[196:199], v[24:27]
	v_mfma_f32_16x16x32_bf16 v[16:19], v[162:165], v[196:199], v[16:19]
	v_mfma_f32_16x16x32_bf16 v[8:11], v[144:147], v[226:229], v[8:11]
	v_mfma_f32_16x16x32_bf16 v[0:3], v[162:165], v[226:229], v[0:3]
	v_mfma_f32_16x16x32_bf16 v[56:59], v[148:151], v[174:177], v[56:59]
	v_mfma_f32_16x16x32_bf16 v[48:51], v[166:169], v[174:177], v[48:51]
	v_mfma_f32_16x16x32_bf16 v[40:43], v[148:151], v[192:195], v[40:43]
	v_mfma_f32_16x16x32_bf16 v[32:35], v[166:169], v[192:195], v[32:35]
	v_mfma_f32_16x16x32_bf16 v[24:27], v[148:151], v[222:225], v[24:27]
	v_mfma_f32_16x16x32_bf16 v[16:19], v[166:169], v[222:225], v[16:19]
	v_mfma_f32_16x16x32_bf16 v[8:11], v[148:151], v[230:233], v[8:11]
	v_mfma_f32_16x16x32_bf16 v[0:3], v[166:169], v[230:233], v[0:3]
	s_setprio 0
	s_barrier
	s_add_u32 s62, s62, 0x100
	s_addc_u32 s63, s63, 0
	s_add_u32 s74, s74, 0x100
	s_addc_u32 s75, s75, 0
	s_cmp_ge_i32 s76, s21
	s_mov_b32 s64, s76
	s_cbranch_scc0 .LBB0_1256

; #define PG8_STAGE(bufoff, gbase, voff) do { _Pragma("unroll") for (int _i = 0; _i < 2; ++_i) \
;         __builtin_amdgcn_global_load_lds((const unsigned*)((const char*)(gbase) + (voff)[_i]), (LAS unsigned*)(lds + (bufoff) + ldsw + _i * 8192), 16, 0, 0); } while (0)
; #define PG8_LDA(dst, b, h) do { _Pragma("unroll") for (int m = 0; m < 4; ++m) _Pragma("unroll") for (int k = 0; k < 2; ++k) dst[m][k] = *(const LAS bf16x8*)(lds + PG8_SA(b, h) + aoff + m * 2048 + k * 1024); } while (0)
; #define PG8_LDB(dst, b, h) do { _Pragma("unroll") for (int n = 0; n < 2; ++n) _Pragma("unroll") for (int k = 0; k < 2; ++k) dst[n][k] = *(const LAS bf16x8*)(lds + PG8_SB(b, h) + boff + n * 2048 + k * 1024); } while (0)
; #define PG8_MMA(ai, bj, At, Bt) do { __builtin_amdgcn_s_setprio(1); _Pragma("unroll") for (int m = 0; m < 4; ++m) _Pragma("unroll") for (int n = 0; n < 2; ++n) _Pragma("unroll") for (int k = 0; k < 2; ++k) \
;         acc[ai][bj][m][n] = __builtin_amdgcn_mfma_f32_16x16x32_bf16(Bt[n][k], At[m][k], acc[ai][bj][m][n], 0, 0, 0); __builtin_amdgcn_s_setprio(0); } while (0)
; #define PG8_WAIT_V(n) asm volatile("s_waitcnt vmcnt(" #n ")" ::: "memory")
; #define PG8_WAIT_L(n) asm volatile("s_waitcnt lgkmcnt(" #n ")" ::: "memory")
; #define PG8_BAR __builtin_amdgcn_s_barrier()
; #define PG8_SCHED __builtin_amdgcn_sched_barrier(0)
; template <class Epi, class Addr>
; __device__ __forceinline__ void gemm_phase(LAS unsigned char* lds, const Gemm g, const StaticOrder& S, const Addr& AD, const Epi& E) {
;     ...
;             PG8_LDB(B0, 0, 0); PG8_LDB(B1, 0, 1); PG8_SCHED; PG8_LDA(At, 0, 0); PG8_STAGE(PG8_SA(1, 1), a1 + hstepA, voffA);
;             PG8_WAIT_V(8); PG8_WAIT_L(0); PG8_BAR; PG8_MMA(0, 0, At, B0); PG8_MMA(0, 1, At, B1); PG8_BAR; PG8_SCHED;
;             PG8_LDA(At, 0, 1); PG8_STAGE(PG8_SB(0, 0), b2, voffB); PG8_STAGE(PG8_SB(0, 1), b2 + hstepB, voffB); PG8_STAGE(PG8_SA(0, 0), a2, voffA);
;             PG8_WAIT_V(8); PG8_WAIT_L(0); PG8_BAR; PG8_MMA(1, 0, At, B0); PG8_MMA(1, 1, At, B1); PG8_BAR; PG8_SCHED;
.LBB0_1332:
	s_add_i32 s81, s66, 2
	s_add_u32 s6, s8, 0x100
	s_addc_u32 s7, s9, 0
	s_add_i32 s24, 0, 0x10000
	s_cmp_eq_u32 s74, s66
	s_cselect_b32 s69, s63, s7
	s_cselect_b32 s68, s62, s6
	s_cselect_b32 s67, s65, s80
	s_cselect_b32 s66, s64, s79
	s_add_i32 s25, 0, 0x14000
	v_add_u32_e32 v146, s24, v242
	v_add_u32_e32 v162, s25, v242
	ds_read_b128 v[134:137], v146
	ds_read_b128 v[138:141], v146 offset:1024
	ds_read_b128 v[142:145], v146 offset:2048
	ds_read_b128 v[146:149], v146 offset:3072
	ds_read_b128 v[150:153], v162
	ds_read_b128 v[154:157], v162 offset:1024
	ds_read_b128 v[158:161], v162 offset:2048
	ds_read_b128 v[162:165], v162 offset:3072
	s_add_i32 m0, s17, 0xc000
	ds_read_b128 v[166:169], v243
	ds_read_b128 v[170:173], v243 offset:1024
	ds_read_b128 v[174:177], v243 offset:2048
	ds_read_b128 v[178:181], v243 offset:3072
	ds_read_b128 v[182:185], v243 offset:4096
	ds_read_b128 v[186:189], v243 offset:5120
	ds_read_b128 v[190:193], v243 offset:6144
	ds_read_b128 v[194:197], v243 offset:7168
	global_load_lds_dwordx4 v130, s[8:9]
	s_add_i32 m0, s17, 0xe000
	s_nop 0
	global_load_lds_dwordx4 v132, s[8:9]
	s_waitcnt vmcnt(8)
	s_waitcnt lgkmcnt(0)
	s_barrier
	s_setprio 1
	s_waitcnt lgkmcnt(0)
	v_mfma_f32_16x16x32_bf16 v[124:127], v[134:137], v[166:169], v[124:127]
	v_mfma_f32_16x16x32_bf16 v[120:123], v[142:145], v[166:169], v[120:123]
	v_mfma_f32_16x16x32_bf16 v[116:119], v[134:137], v[174:177], v[116:119]
	v_mfma_f32_16x16x32_bf16 v[112:115], v[142:145], v[174:177], v[112:115]
	v_mfma_f32_16x16x32_bf16 v[104:107], v[134:137], v[182:185], v[104:107]
	v_mfma_f32_16x16x32_bf16 v[96:99], v[142:145], v[182:185], v[96:99]
	v_mfma_f32_16x16x32_bf16 v[88:91], v[134:137], v[190:193], v[88:91]
	v_mfma_f32_16x16x32_bf16 v[80:83], v[142:145], v[190:193], v[80:83]
	v_mfma_f32_16x16x32_bf16 v[124:127], v[138:141], v[170:173], v[124:127]
	v_mfma_f32_16x16x32_bf16 v[120:123], v[146:149], v[170:173], v[120:123]
	v_mfma_f32_16x16x32_bf16 v[116:119], v[138:141], v[178:181], v[116:119]
	v_mfma_f32_16x16x32_bf16 v[112:115], v[146:149], v[178:181], v[112:115]
	v_mfma_f32_16x16x32_bf16 v[104:107], v[138:141], v[186:189], v[104:107]
	v_mfma_f32_16x16x32_bf16 v[96:99], v[146:149], v[186:189], v[96:99]
	v_mfma_f32_16x16x32_bf16 v[88:91], v[138:141], v[194:197], v[88:91]
	v_mfma_f32_16x16x32_bf16 v[80:83], v[146:149], v[194:197], v[80:83]
	s_setprio 0
	s_setprio 1
	v_mfma_f32_16x16x32_bf16 v[108:111], v[150:153], v[166:169], v[108:111]
	v_mfma_f32_16x16x32_bf16 v[100:103], v[158:161], v[166:169], v[100:103]
	v_mfma_f32_16x16x32_bf16 v[92:95], v[150:153], v[174:177], v[92:95]
	v_mfma_f32_16x16x32_bf16 v[84:87], v[158:161], v[174:177], v[84:87]
	v_mfma_f32_16x16x32_bf16 v[76:79], v[150:153], v[182:185], v[76:79]
	v_mfma_f32_16x16x32_bf16 v[72:75], v[158:161], v[182:185], v[72:75]
	v_mfma_f32_16x16x32_bf16 v[68:71], v[150:153], v[190:193], v[68:71]
	v_mfma_f32_16x16x32_bf16 v[64:67], v[158:161], v[190:193], v[64:67]
	v_mfma_f32_16x16x32_bf16 v[108:111], v[154:157], v[170:173], v[108:111]
	v_mfma_f32_16x16x32_bf16 v[100:103], v[162:165], v[170:173], v[100:103]
	v_mfma_f32_16x16x32_bf16 v[92:95], v[154:157], v[178:181], v[92:95]
	v_mfma_f32_16x16x32_bf16 v[84:87], v[162:165], v[178:181], v[84:87]
	v_mfma_f32_16x16x32_bf16 v[76:79], v[154:157], v[186:189], v[76:79]
	v_mfma_f32_16x16x32_bf16 v[72:75], v[162:165], v[186:189], v[72:75]
	v_mfma_f32_16x16x32_bf16 v[68:71], v[154:157], v[194:197], v[68:71]
	v_mfma_f32_16x16x32_bf16 v[64:67], v[162:165], v[194:197], v[64:67]
	s_setprio 0
	s_barrier
	s_add_i32 s8, s24, s2
	s_mov_b32 m0, s8
	ds_read_b128 v[166:169], v243 offset:16384
	ds_read_b128 v[170:173], v243 offset:17408
	ds_read_b128 v[174:177], v243 offset:18432
	ds_read_b128 v[178:181], v243 offset:19456
	ds_read_b128 v[182:185], v243 offset:20480
	ds_read_b128 v[186:189], v243 offset:21504
	ds_read_b128 v[190:193], v243 offset:22528
	ds_read_b128 v[194:197], v243 offset:23552
	global_load_lds_dwordx4 v200, s[66:67]
	s_add_i32 m0, s8, 0x2000
	s_add_u32 s8, s66, 0xb0000
	s_addc_u32 s9, s67, 0
	s_add_i32 s24, s25, s2
	global_load_lds_dwordx4 v128, s[66:67]
	s_mov_b32 m0, s24
	s_nop 0
	global_load_lds_dwordx4 v200, s[8:9]
	s_add_i32 m0, s24, 0x2000
	s_nop 0
	global_load_lds_dwordx4 v128, s[8:9]
	s_mov_b32 m0, s17
	s_nop 0
	global_load_lds_dwordx4 v200, s[68:69]
	s_mov_b32 m0, s18
	s_nop 0
	global_load_lds_dwordx4 v128, s[68:69]
	s_waitcnt vmcnt(8)
	s_waitcnt lgkmcnt(0)
	s_barrier
	s_setprio 1
	s_waitcnt lgkmcnt(0)
	v_mfma_f32_16x16x32_bf16 v[60:63], v[134:137], v[166:169], v[60:63]
	v_mfma_f32_16x16x32_bf16 v[56:59], v[142:145], v[166:169], v[56:59]
	v_mfma_f32_16x16x32_bf16 v[52:55], v[134:137], v[174:177], v[52:55]
	v_mfma_f32_16x16x32_bf16 v[48:51], v[142:145], v[174:177], v[48:51]
	v_mfma_f32_16x16x32_bf16 v[40:43], v[134:137], v[182:185], v[40:43]
	v_mfma_f32_16x16x32_bf16 v[32:35], v[142:145], v[182:185], v[32:35]
	v_mfma_f32_16x16x32_bf16 v[24:27], v[134:137], v[190:193], v[24:27]
	v_mfma_f32_16x16x32_bf16 v[16:19], v[142:145], v[190:193], v[16:19]
	v_mfma_f32_16x16x32_bf16 v[60:63], v[138:141], v[170:173], v[60:63]
	v_mfma_f32_16x16x32_bf16 v[56:59], v[146:149], v[170:173], v[56:59]
	v_mfma_f32_16x16x32_bf16 v[52:55], v[138:141], v[178:181], v[52:55]
	v_mfma_f32_16x16x32_bf16 v[48:51], v[146:149], v[178:181], v[48:51]
	v_mfma_f32_16x16x32_bf16 v[40:43], v[138:141], v[186:189], v[40:43]
	v_mfma_f32_16x16x32_bf16 v[32:35], v[146:149], v[186:189], v[32:35]
	v_mfma_f32_16x16x32_bf16 v[24:27], v[138:141], v[194:197], v[24:27]
	v_mfma_f32_16x16x32_bf16 v[16:19], v[146:149], v[194:197], v[16:19]
	s_setprio 0
	s_setprio 1
	v_mfma_f32_16x16x32_bf16 v[44:47], v[150:153], v[166:169], v[44:47]
	v_mfma_f32_16x16x32_bf16 v[36:39], v[158:161], v[166:169], v[36:39]
	v_mfma_f32_16x16x32_bf16 v[28:31], v[150:153], v[174:177], v[28:31]
	v_mfma_f32_16x16x32_bf16 v[20:23], v[158:161], v[174:177], v[20:23]
	v_mfma_f32_16x16x32_bf16 v[12:15], v[150:153], v[182:185], v[12:15]
	v_mfma_f32_16x16x32_bf16 v[8:11], v[158:161], v[182:185], v[8:11]
	v_mfma_f32_16x16x32_bf16 v[4:7], v[150:153], v[190:193], v[4:7]
	v_mfma_f32_16x16x32_bf16 v[0:3], v[158:161], v[190:193], v[0:3]
	v_mfma_f32_16x16x32_bf16 v[44:47], v[154:157], v[170:173], v[44:47]
	v_mfma_f32_16x16x32_bf16 v[36:39], v[162:165], v[170:173], v[36:39]
	v_mfma_f32_16x16x32_bf16 v[28:31], v[154:157], v[178:181], v[28:31]
	v_mfma_f32_16x16x32_bf16 v[20:23], v[162:165], v[178:181], v[20:23]
	v_mfma_f32_16x16x32_bf16 v[12:15], v[154:157], v[186:189], v[12:15]
	v_mfma_f32_16x16x32_bf16 v[8:11], v[162:165], v[186:189], v[8:11]
	v_mfma_f32_16x16x32_bf16 v[4:7], v[154:157], v[194:197], v[4:7]
	v_mfma_f32_16x16x32_bf16 v[0:3], v[162:165], v[194:197], v[0:3]
	s_setprio 0
	s_barrier
; #define PG8_STAGE(bufoff, gbase, voff) do { _Pragma("unroll") for (int _i = 0; _i < 2; ++_i) \
;         __builtin_amdgcn_global_load_lds((const unsigned*)((const char*)(gbase) + (voff)[_i]), (LAS unsigned*)(lds + (bufoff) + ldsw + _i * 8192), 16, 0, 0); } while (0)
; #define PG8_LDA(dst, b, h) do { _Pragma("unroll") for (int m = 0; m < 4; ++m) _Pragma("unroll") for (int k = 0; k < 2; ++k) dst[m][k] = *(const LAS bf16x8*)(lds + PG8_SA(b, h) + aoff + m * 2048 + k * 1024); } while (0)
; #define PG8_LDB(dst, b, h) do { _Pragma("unroll") for (int n = 0; n < 2; ++n) _Pragma("unroll") for (int k = 0; k < 2; ++k) dst[n][k] = *(const LAS bf16x8*)(lds + PG8_SB(b, h) + boff + n * 2048 + k * 1024); } while (0)
; #define PG8_MMA(ai, bj, At, Bt) do { __builtin_amdgcn_s_setprio(1); _Pragma("unroll") for (int m = 0; m < 4; ++m) _Pragma("unroll") for (int n = 0; n < 2; ++n) _Pragma("unroll") for (int k = 0; k < 2; ++k) \
;         acc[ai][bj][m][n] = __builtin_amdgcn_mfma_f32_16x16x32_bf16(Bt[n][k], At[m][k], acc[ai][bj][m][n], 0, 0, 0); __builtin_amdgcn_s_setprio(0); } while (0)
; #define PG8_WAIT_V(n) asm volatile("s_waitcnt vmcnt(" #n ")" ::: "memory")
; #define PG8_WAIT_L(n) asm volatile("s_waitcnt lgkmcnt(" #n ")" ::: "memory")
; #define PG8_BAR __builtin_amdgcn_s_barrier()
; #define PG8_SCHED __builtin_amdgcn_sched_barrier(0)
; template <class Epi, class Addr>
; __device__ __forceinline__ void gemm_phase(LAS unsigned char* lds, const Gemm g, const StaticOrder& S, const Addr& AD, const Epi& E) {
;     ...
;             PG8_LDB(B0, 1, 0); PG8_LDB(B1, 1, 1); PG8_SCHED; PG8_LDA(At, 1, 0); PG8_STAGE(PG8_SA(0, 1), a2 + hstepA, voffA);
;             PG8_WAIT_V(8); PG8_WAIT_L(0); PG8_BAR; PG8_MMA(0, 0, At, B0); PG8_MMA(0, 1, At, B1); PG8_BAR; PG8_SCHED;
;             PG8_LDA(At, 1, 1); PG8_STAGE(PG8_SB(1, 0), b3, voffB); PG8_STAGE(PG8_SB(1, 1), b3 + hstepB, voffB); PG8_STAGE(PG8_SA(1, 0), a3, voffA);
;             PG8_WAIT_V(8); PG8_WAIT_L(0); PG8_BAR; PG8_MMA(1, 0, At, B0); PG8_MMA(1, 1, At, B1); PG8_BAR; PG8_SCHED;
	s_add_i32 s24, 0, 0x18000
	s_add_i32 s25, 0, 0x1c000
	v_add_u32_e32 v146, s24, v242
	v_add_u32_e32 v162, s25, v242
	ds_read_b128 v[134:137], v146
	ds_read_b128 v[138:141], v146 offset:1024
	ds_read_b128 v[142:145], v146 offset:2048
	ds_read_b128 v[146:149], v146 offset:3072
	ds_read_b128 v[150:153], v162
	ds_read_b128 v[154:157], v162 offset:1024
	ds_read_b128 v[158:161], v162 offset:2048
	ds_read_b128 v[162:165], v162 offset:3072
	s_add_u32 s8, s68, 0xb0000
	s_addc_u32 s9, s69, 0
	s_mov_b32 m0, s19
	ds_read_b128 v[166:169], v243 offset:32768
	ds_read_b128 v[170:173], v243 offset:33792
	ds_read_b128 v[174:177], v243 offset:34816
	ds_read_b128 v[178:181], v243 offset:35840
	ds_read_b128 v[182:185], v243 offset:36864
	ds_read_b128 v[186:189], v243 offset:37888
	ds_read_b128 v[190:193], v243 offset:38912
	ds_read_b128 v[194:197], v243 offset:39936
	global_load_lds_dwordx4 v200, s[8:9]
	s_mov_b32 m0, s20
	s_nop 0
	global_load_lds_dwordx4 v128, s[8:9]
	s_waitcnt vmcnt(8)
	s_waitcnt lgkmcnt(0)
	s_barrier
	s_setprio 1
	s_waitcnt lgkmcnt(0)
	v_mfma_f32_16x16x32_bf16 v[124:127], v[134:137], v[166:169], v[124:127]
	v_mfma_f32_16x16x32_bf16 v[120:123], v[142:145], v[166:169], v[120:123]
	v_mfma_f32_16x16x32_bf16 v[116:119], v[134:137], v[174:177], v[116:119]
	v_mfma_f32_16x16x32_bf16 v[112:115], v[142:145], v[174:177], v[112:115]
	v_mfma_f32_16x16x32_bf16 v[104:107], v[134:137], v[182:185], v[104:107]
	v_mfma_f32_16x16x32_bf16 v[96:99], v[142:145], v[182:185], v[96:99]
	v_mfma_f32_16x16x32_bf16 v[88:91], v[134:137], v[190:193], v[88:91]
	v_mfma_f32_16x16x32_bf16 v[80:83], v[142:145], v[190:193], v[80:83]
	v_mfma_f32_16x16x32_bf16 v[124:127], v[138:141], v[170:173], v[124:127]
	v_mfma_f32_16x16x32_bf16 v[120:123], v[146:149], v[170:173], v[120:123]
	v_mfma_f32_16x16x32_bf16 v[116:119], v[138:141], v[178:181], v[116:119]
	v_mfma_f32_16x16x32_bf16 v[112:115], v[146:149], v[178:181], v[112:115]
	v_mfma_f32_16x16x32_bf16 v[104:107], v[138:141], v[186:189], v[104:107]
	v_mfma_f32_16x16x32_bf16 v[96:99], v[146:149], v[186:189], v[96:99]
	v_mfma_f32_16x16x32_bf16 v[88:91], v[138:141], v[194:197], v[88:91]
	v_mfma_f32_16x16x32_bf16 v[80:83], v[146:149], v[194:197], v[80:83]
	s_setprio 0
	s_setprio 1
	v_mfma_f32_16x16x32_bf16 v[108:111], v[150:153], v[166:169], v[108:111]
	v_mfma_f32_16x16x32_bf16 v[100:103], v[158:161], v[166:169], v[100:103]
	v_mfma_f32_16x16x32_bf16 v[92:95], v[150:153], v[174:177], v[92:95]
	v_mfma_f32_16x16x32_bf16 v[84:87], v[158:161], v[174:177], v[84:87]
	v_mfma_f32_16x16x32_bf16 v[76:79], v[150:153], v[182:185], v[76:79]
	v_mfma_f32_16x16x32_bf16 v[72:75], v[158:161], v[182:185], v[72:75]
	v_mfma_f32_16x16x32_bf16 v[68:71], v[150:153], v[190:193], v[68:71]
	v_mfma_f32_16x16x32_bf16 v[64:67], v[158:161], v[190:193], v[64:67]
	v_mfma_f32_16x16x32_bf16 v[108:111], v[154:157], v[170:173], v[108:111]
	v_mfma_f32_16x16x32_bf16 v[100:103], v[162:165], v[170:173], v[100:103]
	v_mfma_f32_16x16x32_bf16 v[92:95], v[154:157], v[178:181], v[92:95]
	v_mfma_f32_16x16x32_bf16 v[84:87], v[162:165], v[178:181], v[84:87]
	v_mfma_f32_16x16x32_bf16 v[76:79], v[154:157], v[186:189], v[76:79]
	v_mfma_f32_16x16x32_bf16 v[72:75], v[162:165], v[186:189], v[72:75]
	v_mfma_f32_16x16x32_bf16 v[68:71], v[154:157], v[194:197], v[68:71]
	v_mfma_f32_16x16x32_bf16 v[64:67], v[162:165], v[194:197], v[64:67]
	s_setprio 0
	s_barrier
	s_add_i32 s8, s24, s2
	s_mov_b32 m0, s8
	s_add_u32 s8, s66, 0x80
	s_addc_u32 s9, s67, 0
	ds_read_b128 v[166:169], v243 offset:49152
	ds_read_b128 v[170:173], v243 offset:50176
	ds_read_b128 v[174:177], v243 offset:51200
	ds_read_b128 v[178:181], v243 offset:52224
	ds_read_b128 v[182:185], v243 offset:53248
	ds_read_b128 v[186:189], v243 offset:54272
	ds_read_b128 v[190:193], v243 offset:55296
	ds_read_b128 v[194:197], v243 offset:56320
	global_load_lds_dwordx4 v200, s[8:9]
	s_add_i32 m0, m0, 0x2000
	s_add_i32 s24, s25, s2
	s_nop 0
	global_load_lds_dwordx4 v128, s[8:9]
	s_add_u32 s8, s66, 0xb0080
	s_addc_u32 s9, s67, 0
	s_mov_b32 m0, s24
	s_nop 0
	global_load_lds_dwordx4 v200, s[8:9]
	s_add_i32 m0, s24, 0x2000
	s_nop 0
	global_load_lds_dwordx4 v128, s[8:9]
	s_add_u32 s8, s68, 0x80
	s_addc_u32 s9, s69, 0
	s_mov_b32 m0, s72
	s_nop 0
	global_load_lds_dwordx4 v200, s[8:9]
	s_mov_b32 m0, s73
	s_nop 0
	global_load_lds_dwordx4 v128, s[8:9]
	s_waitcnt vmcnt(8)
	s_waitcnt lgkmcnt(0)
	s_barrier
; #define PG8_STAGE(bufoff, gbase, voff) do { _Pragma("unroll") for (int _i = 0; _i < 2; ++_i) \
;         __builtin_amdgcn_global_load_lds((const unsigned*)((const char*)(gbase) + (voff)[_i]), (LAS unsigned*)(lds + (bufoff) + ldsw + _i * 8192), 16, 0, 0); } while (0)
; #define PG8_LDA(dst, b, h) do { _Pragma("unroll") for (int m = 0; m < 4; ++m) _Pragma("unroll") for (int k = 0; k < 2; ++k) dst[m][k] = *(const LAS bf16x8*)(lds + PG8_SA(b, h) + aoff + m * 2048 + k * 1024); } while (0)
; #define PG8_MMA(ai, bj, At, Bt) do { __builtin_amdgcn_s_setprio(1); _Pragma("unroll") for (int m = 0; m < 4; ++m) _Pragma("unroll") for (int n = 0; n < 2; ++n) _Pragma("unroll") for (int k = 0; k < 2; ++k) \
;         acc[ai][bj][m][n] = __builtin_amdgcn_mfma_f32_16x16x32_bf16(Bt[n][k], At[m][k], acc[ai][bj][m][n], 0, 0, 0); __builtin_amdgcn_s_setprio(0); } while (0)
; #define PG8_WAIT_V(n) asm volatile("s_waitcnt vmcnt(" #n ")" ::: "memory")
; #define PG8_WAIT_L(n) asm volatile("s_waitcnt lgkmcnt(" #n ")" ::: "memory")
; #define PG8_BAR __builtin_amdgcn_s_barrier()
; #define PG8_SCHED __builtin_amdgcn_sched_barrier(0)
;     __device__ __forceinline__ void operator()(Acc& acc, const Unit& u, int wr, int wc, int fr, int fq, LAS unsigned char* xch) const {
;     ...
;             for (int q = 0; q < 4; ++q) v[q] = pre[g % PD][q] + acc[ai][q >> 1][m][q & 1] * alpha;
; template <class Epi, class Addr>
; __device__ __forceinline__ void gemm_phase(LAS unsigned char* lds, const Gemm g, const StaticOrder& S, const Addr& AD, const Epi& E) {
;     ...
;             PG8_WAIT_V(8); PG8_WAIT_L(0); PG8_BAR; PG8_MMA(0, 0, At, B0); PG8_MMA(0, 1, At, B1); PG8_BAR; PG8_SCHED;
;             PG8_LDA(At, 1, 1); PG8_STAGE(PG8_SB(1, 0), b3, voffB); PG8_STAGE(PG8_SB(1, 1), b3 + hstepB, voffB); PG8_STAGE(PG8_SA(1, 0), a3, voffA);
;             PG8_WAIT_V(8); PG8_WAIT_L(0); PG8_BAR; PG8_MMA(1, 0, At, B0); PG8_MMA(1, 1, At, B1); PG8_BAR; PG8_SCHED;
;         }
	s_setprio 1
	s_waitcnt lgkmcnt(0)
	v_mfma_f32_16x16x32_bf16 v[60:63], v[134:137], v[166:169], v[60:63]
	v_mfma_f32_16x16x32_bf16 v[56:59], v[142:145], v[166:169], v[56:59]
	v_mfma_f32_16x16x32_bf16 v[52:55], v[134:137], v[174:177], v[52:55]
	v_mfma_f32_16x16x32_bf16 v[48:51], v[142:145], v[174:177], v[48:51]
	v_mfma_f32_16x16x32_bf16 v[40:43], v[134:137], v[182:185], v[40:43]
	v_mfma_f32_16x16x32_bf16 v[32:35], v[142:145], v[182:185], v[32:35]
	v_mfma_f32_16x16x32_bf16 v[24:27], v[134:137], v[190:193], v[24:27]
	v_mfma_f32_16x16x32_bf16 v[16:19], v[142:145], v[190:193], v[16:19]
	v_mfma_f32_16x16x32_bf16 v[60:63], v[138:141], v[170:173], v[60:63]
	v_mfma_f32_16x16x32_bf16 v[56:59], v[146:149], v[170:173], v[56:59]
	v_mfma_f32_16x16x32_bf16 v[52:55], v[138:141], v[178:181], v[52:55]
	v_mfma_f32_16x16x32_bf16 v[48:51], v[146:149], v[178:181], v[48:51]
	v_mfma_f32_16x16x32_bf16 v[40:43], v[138:141], v[186:189], v[40:43]
	v_mfma_f32_16x16x32_bf16 v[32:35], v[146:149], v[186:189], v[32:35]
	v_mfma_f32_16x16x32_bf16 v[24:27], v[138:141], v[194:197], v[24:27]
	v_mfma_f32_16x16x32_bf16 v[16:19], v[146:149], v[194:197], v[16:19]
	s_setprio 0
	s_setprio 1
	v_mfma_f32_16x16x32_bf16 v[44:47], v[150:153], v[166:169], v[44:47]
	v_mfma_f32_16x16x32_bf16 v[36:39], v[158:161], v[166:169], v[36:39]
	v_mfma_f32_16x16x32_bf16 v[28:31], v[150:153], v[174:177], v[28:31]
	v_mfma_f32_16x16x32_bf16 v[20:23], v[158:161], v[174:177], v[20:23]
	v_mfma_f32_16x16x32_bf16 v[12:15], v[150:153], v[182:185], v[12:15]
	v_mfma_f32_16x16x32_bf16 v[8:11], v[158:161], v[182:185], v[8:11]
	v_mfma_f32_16x16x32_bf16 v[4:7], v[150:153], v[190:193], v[4:7]
	v_mfma_f32_16x16x32_bf16 v[0:3], v[158:161], v[190:193], v[0:3]
	v_mfma_f32_16x16x32_bf16 v[44:47], v[154:157], v[170:173], v[44:47]
	v_mfma_f32_16x16x32_bf16 v[36:39], v[162:165], v[170:173], v[36:39]
	v_mfma_f32_16x16x32_bf16 v[28:31], v[154:157], v[178:181], v[28:31]
	v_mfma_f32_16x16x32_bf16 v[20:23], v[162:165], v[178:181], v[20:23]
	v_mfma_f32_16x16x32_bf16 v[12:15], v[154:157], v[186:189], v[12:15]
	v_mfma_f32_16x16x32_bf16 v[8:11], v[162:165], v[186:189], v[8:11]
	v_mfma_f32_16x16x32_bf16 v[4:7], v[154:157], v[194:197], v[4:7]
	v_mfma_f32_16x16x32_bf16 v[0:3], v[162:165], v[194:197], v[0:3]
	s_setprio 0
	s_barrier
	s_add_u32 s79, s79, 0x100
	s_addc_u32 s80, s80, 0
	s_cmp_ge_i32 s81, s23
	s_mov_b64 s[8:9], s[6:7]
	s_mov_b32 s66, s81
	s_cbranch_scc0 .LBB0_1332
	v_pk_mul_f32 v[188:189], v[126:127], 0.5 op_sel_hi:[1,0]
	v_pk_mul_f32 v[226:227], v[124:125], 0.5 op_sel_hi:[1,0]
	v_pk_mul_f32 v[196:197], v[122:123], 0.5 op_sel_hi:[1,0]
	v_pk_mul_f32 v[194:195], v[120:121], 0.5 op_sel_hi:[1,0]
	v_pk_mul_f32 v[222:223], v[110:111], 0.5 op_sel_hi:[1,0]
	v_pk_mul_f32 v[198:199], v[108:109], 0.5 op_sel_hi:[1,0]
	v_pk_mul_f32 v[192:193], v[102:103], 0.5 op_sel_hi:[1,0]
	v_pk_mul_f32 v[190:191], v[100:101], 0.5 op_sel_hi:[1,0]
	v_pk_mul_f32 v[184:185], v[118:119], 0.5 op_sel_hi:[1,0]
	v_pk_mul_f32 v[186:187], v[116:117], 0.5 op_sel_hi:[1,0]
	v_pk_mul_f32 v[178:179], v[114:115], 0.5 op_sel_hi:[1,0]
	v_pk_mul_f32 v[176:177], v[112:113], 0.5 op_sel_hi:[1,0]
	v_pk_mul_f32 v[182:183], v[94:95], 0.5 op_sel_hi:[1,0]
	v_pk_mul_f32 v[180:181], v[92:93], 0.5 op_sel_hi:[1,0]
	v_pk_mul_f32 v[170:171], v[86:87], 0.5 op_sel_hi:[1,0]
	v_pk_mul_f32 v[168:169], v[84:85], 0.5 op_sel_hi:[1,0]
	v_pk_mul_f32 v[164:165], v[106:107], 0.5 op_sel_hi:[1,0]
	v_pk_mul_f32 v[166:167], v[104:105], 0.5 op_sel_hi:[1,0]
	v_pk_mul_f32 v[158:159], v[98:99], 0.5 op_sel_hi:[1,0]
	v_pk_mul_f32 v[156:157], v[96:97], 0.5 op_sel_hi:[1,0]
	v_pk_mul_f32 v[162:163], v[78:79], 0.5 op_sel_hi:[1,0]
	v_pk_mul_f32 v[160:161], v[76:77], 0.5 op_sel_hi:[1,0]
	v_pk_mul_f32 v[154:155], v[74:75], 0.5 op_sel_hi:[1,0]
	v_pk_mul_f32 v[152:153], v[72:73], 0.5 op_sel_hi:[1,0]
	v_pk_mul_f32 v[148:149], v[90:91], 0.5 op_sel_hi:[1,0]
	v_pk_mul_f32 v[150:151], v[88:89], 0.5 op_sel_hi:[1,0]
	v_pk_mul_f32 v[142:143], v[82:83], 0.5 op_sel_hi:[1,0]
	v_pk_mul_f32 v[140:141], v[80:81], 0.5 op_sel_hi:[1,0]
	v_pk_mul_f32 v[146:147], v[70:71], 0.5 op_sel_hi:[1,0]
	v_pk_mul_f32 v[144:145], v[68:69], 0.5 op_sel_hi:[1,0]
	v_pk_mul_f32 v[138:139], v[66:67], 0.5 op_sel_hi:[1,0]
	v_pk_mul_f32 v[136:137], v[64:65], 0.5 op_sel_hi:[1,0]
	v_pk_mul_f32 v[126:127], v[62:63], 0.5 op_sel_hi:[1,0]
	v_pk_mul_f32 v[134:135], v[60:61], 0.5 op_sel_hi:[1,0]
	v_pk_mul_f32 v[118:119], v[58:59], 0.5 op_sel_hi:[1,0]
	v_pk_mul_f32 v[116:117], v[56:57], 0.5 op_sel_hi:[1,0]
	v_pk_mul_f32 v[122:123], v[46:47], 0.5 op_sel_hi:[1,0]
	v_pk_mul_f32 v[120:121], v[44:45], 0.5 op_sel_hi:[1,0]
	v_pk_mul_f32 v[114:115], v[38:39], 0.5 op_sel_hi:[1,0]
	v_pk_mul_f32 v[112:113], v[36:37], 0.5 op_sel_hi:[1,0]
	v_pk_mul_f32 v[110:111], v[54:55], 0.5 op_sel_hi:[1,0]
	v_pk_mul_f32 v[108:109], v[52:53], 0.5 op_sel_hi:[1,0]
	v_pk_mul_f32 v[102:103], v[50:51], 0.5 op_sel_hi:[1,0]
	v_pk_mul_f32 v[100:101], v[48:49], 0.5 op_sel_hi:[1,0]
	v_pk_mul_f32 v[106:107], v[30:31], 0.5 op_sel_hi:[1,0]
	v_pk_mul_f32 v[104:105], v[28:29], 0.5 op_sel_hi:[1,0]
	v_pk_mul_f32 v[98:99], v[22:23], 0.5 op_sel_hi:[1,0]
	v_pk_mul_f32 v[96:97], v[20:21], 0.5 op_sel_hi:[1,0]
	v_pk_mul_f32 v[94:95], v[42:43], 0.5 op_sel_hi:[1,0]
	v_pk_mul_f32 v[92:93], v[40:41], 0.5 op_sel_hi:[1,0]
	v_pk_mul_f32 v[86:87], v[34:35], 0.5 op_sel_hi:[1,0]
	v_pk_mul_f32 v[84:85], v[32:33], 0.5 op_sel_hi:[1,0]
	v_pk_mul_f32 v[90:91], v[14:15], 0.5 op_sel_hi:[1,0]
	v_pk_mul_f32 v[88:89], v[12:13], 0.5 op_sel_hi:[1,0]
	v_pk_mul_f32 v[82:83], v[10:11], 0.5 op_sel_hi:[1,0]
	v_pk_mul_f32 v[80:81], v[8:9], 0.5 op_sel_hi:[1,0]
	v_pk_mul_f32 v[78:79], v[26:27], 0.5 op_sel_hi:[1,0]
	v_pk_mul_f32 v[76:77], v[24:25], 0.5 op_sel_hi:[1,0]
	v_pk_mul_f32 v[70:71], v[18:19], 0.5 op_sel_hi:[1,0]
	v_pk_mul_f32 v[68:69], v[16:17], 0.5 op_sel_hi:[1,0]
	v_pk_mul_f32 v[74:75], v[6:7], 0.5 op_sel_hi:[1,0]
	v_pk_mul_f32 v[72:73], v[4:5], 0.5 op_sel_hi:[1,0]
	v_pk_mul_f32 v[66:67], v[2:3], 0.5 op_sel_hi:[1,0]
	v_pk_mul_f32 v[64:65], v[0:1], 0.5 op_sel_hi:[1,0]
